# attention: softmax row sums accumulated per lane in f32 VALU (instead of an extra P x ones MFMA per key step), transposed once per unit through the wave scratch
# speedup vs baseline: 1.0030x; 1.0020x over previous
; #define LAS __attribute__((address_space(3)))
; #define GAS __attribute__((address_space(1)))
; #define AT_LOAD(t) do { const GAS u32x4* Kg_ = (const GAS u32x4*)(Kp + (size_t)(t) * 128 * DK); const GAS u32x4* Vg_ = (const GAS u32x4*)(Vp + (size_t)(t) * 128 * 64); \
;         _Pragma("unroll") for (int i_ = 0; i_ < NKC; ++i_) kreg[i_] = Kg_[tid + 512 * i_]; vreg[0] = Vg_[tid]; vreg[1] = Vg_[tid + 512]; } while (0)
; #define AT_STORE(bf_) do { LAS unsigned char* nb_ = lds + (bf_) * AT_KBUF; _Pragma("unroll") for (int i_ = 0; i_ < NKC; ++i_) *(LAS u32x4*)(nb_ + koff[i_]) = kreg[i_]; \
;         *(LAS u32x4*)(lds + (bf_) * AT_VBUF + voff[0]) = vreg[0]; *(LAS u32x4*)(lds + (bf_) * AT_VBUF + voff[1]) = vreg[1]; } while (0)
; template <int DK>
; __device__ __forceinline__ void attn_unit(LAS unsigned char* lds, const GAS bf16* Qp, const GAS bf16* Kp, const GAS bf16* Vp, GAS bf16* Yp, int b, int j, int nkeys, int tid, int lane, int wave) {
;     ...
;     { const GAS bf16* Qw = Qp + (size_t)(256 * j + wave * 32 + r32) * DK + hi * 8;
; #pragma unroll
;       for (int d0 = 0; d0 < ND; ++d0) qr[d0] = *(const GAS bf16x8*)(Qw + d0 * 16); }
;     int koff[NKC], voff[2];
; #pragma unroll
;     for (int i = 0; i < NKC; ++i) { const int kc = tid + 512 * i; koff[i] = (kc / CPR) * KSTR + (kc % CPR) * 16; }
; #pragma unroll
;     for (int i = 0; i < 2; ++i) { const int vc = tid + 512 * i, vrow = vc >> 3, vch = vc & 7; voff[i] = AT_VOFF + (vch >> 2) * 8192 + (vrow >> 4) * 1024 + (vrow & 15) * 64 + (vch & 3) * 16; }
;     const int NT = nkeys >> 7;
;     u32x4 kreg[NKC], vreg[2];
;     ...
;     AT_LOAD(0); AT_STORE(0);
;     if (NT > 1) AT_LOAD(1);
;     __syncthreads();
;     LAS float* wsf = (LAS float*)(lds + AT_WSF) + wave * 32;
;     float mhat = 0.f;
;     f32x16 o0, o1, ol, negm;
; #pragma unroll
;     for (int r = 0; r < 16; ++r) { o0[r] = 0.f; o1[r] = 0.f; ol[r] = 0.f; negm[r] = 0.f; }
;     const bf16x8 ones = {0x3F80, 0x3F80, 0x3F80, 0x3F80, 0x3F80, 0x3F80, 0x3F80, 0x3F80};
;     const int kfo = r32 * KSTR + hi * 16;
;     const int vfo = AT_VOFF + (4 * hi + ((lane & 15) >> 2)) * 64 + ((lane >> 4) & 1) * 32 + (lane & 3) * 8;
.LBB0_132:
	s_andn2_b64 vcc, exec, s[22:23]
	s_cbranch_vccnz .LBB0_168
	s_mul_hi_i32 s73, s37, 0x2aaaaaab
	s_lshr_b32 s4, s73, 31
	s_add_i32 s73, s73, s4
	s_mul_i32 s4, s73, 6
	s_sub_i32 s74, s37, s4
	s_cmp_lg_u32 s24, 0
	s_cselect_b64 s[22:23], -1, 0
	s_cmp_eq_u32 s24, 0
	s_cselect_b64 s[44:45], -1, 0
	s_and_b64 s[4:5], s[44:45], exec
	s_movk_i32 s4, 0x100
	v_cmp_eq_u32_e32 vcc, 0, v0
	s_cselect_b32 s4, s4, 0x900
	s_mul_hi_i32 s5, s37, 0x48000
	s_mul_i32 s6, s37, 0x48000
	s_cbranch_vccnz .LBB0_151
	s_mul_i32 s10, s37, 0x6c000
	s_mul_hi_i32 s7, s37, 0x6c000
	s_add_u32 s8, s58, s10
	s_addc_u32 s9, s59, s7
	s_add_u32 s46, s60, s10
	s_addc_u32 s47, s61, s7
	s_add_u32 s48, s64, s6
	s_addc_u32 s49, s65, s5
	s_lshl_b32 s7, s24, 8
	v_readlane_b32 s10, v254, 2
	s_add_i32 s7, s7, s10
	v_or_b32_e32 v0, s7, v231
	v_mov_b64_e32 v[2:3], s[8:9]
	v_mad_i64_i32 v[2:3], s[8:9], v0, s76, v[2:3]
	v_lshl_add_u64 v[4:5], s[46:47], 0, v[206:207]
	s_movk_i32 s8, 0x2000
	v_add_co_u32_e32 v6, vcc, s8, v4
	v_lshl_add_u64 v[2:3], v[200:201], 1, v[2:3]
	s_nop 0
	v_addc_co_u32_e32 v7, vcc, 0, v5, vcc
	s_movk_i32 s9, 0x4000
	global_load_dwordx4 v[144:147], v[2:3], off
	global_load_dwordx4 v[148:151], v[2:3], off offset:32
	global_load_dwordx4 v[152:155], v[2:3], off offset:64
	global_load_dwordx4 v[156:159], v[2:3], off offset:96
	global_load_dwordx4 v[12:15], v[4:5], off
	global_load_dwordx4 v[16:19], v[6:7], off
	v_add_co_u32_e32 v6, vcc, s9, v4
	v_lshl_add_u64 v[8:9], s[48:49], 0, v[206:207]
	s_nop 0
	v_addc_co_u32_e32 v7, vcc, 0, v5, vcc
	global_load_dwordx4 v[20:23], v[6:7], off
	global_load_dwordx4 v[24:27], v[8:9], off
	v_add_co_u32_e32 v6, vcc, s8, v8
	s_movk_i32 s10, 0x6000
	s_nop 0
	v_addc_co_u32_e32 v7, vcc, 0, v9, vcc
	global_load_dwordx4 v[28:31], v[6:7], off
	v_add_co_u32_e32 v6, vcc, s10, v4
	s_mov_b32 s8, 0x8000
	s_nop 0
	v_addc_co_u32_e32 v7, vcc, 0, v5, vcc
	global_load_dwordx4 v[160:163], v[6:7], off
	v_add_co_u32_e32 v6, vcc, s8, v4
	s_mov_b32 s8, 0xa000
	s_nop 0
	v_addc_co_u32_e32 v7, vcc, 0, v5, vcc
	v_add_co_u32_e32 v4, vcc, s8, v4
	v_add_u32_e32 v32, 0, v234
	s_nop 0
	v_addc_co_u32_e32 v5, vcc, 0, v5, vcc
	global_load_dwordx4 v[164:167], v[6:7], off
	global_load_dwordx4 v[176:179], v[4:5], off
	v_add_co_u32_e32 v4, vcc, s9, v8
	v_mov_b32_e32 v0, v1
	s_nop 0
	v_addc_co_u32_e32 v5, vcc, 0, v9, vcc
	v_add_co_u32_e32 v6, vcc, s10, v8
	v_mov_b32_e32 v8, v1
	s_nop 0
	v_addc_co_u32_e32 v7, vcc, 0, v9, vcc
	global_load_dwordx4 v[180:183], v[4:5], off
	global_load_dwordx4 v[184:187], v[6:7], off
	global_load_dwordx4 v[168:171], v[2:3], off offset:128
	global_load_dwordx4 v[172:175], v[2:3], off offset:160
	v_mov_b32_e32 v2, v1
	v_mov_b32_e32 v3, v1
	v_mov_b32_e32 v4, v1
	v_mov_b32_e32 v5, v1
	v_mov_b32_e32 v6, v1
	v_mov_b32_e32 v7, v1
	v_mov_b32_e32 v9, v1
	v_mov_b32_e32 v10, v1
	v_mov_b32_e32 v11, v1
	s_lshr_b32 s8, s4, 7
	v_mov_b32_e32 v248, 0
	s_sub_i32 s9, 0, s8
	s_mov_b32 s10, 2
	v_mov_b32_e32 v64, 0
	v_mov_b32_e32 v65, v248
	v_mov_b32_e32 v66, v248
	v_mov_b32_e32 v67, v248
	v_mov_b32_e32 v68, v248
	v_mov_b32_e32 v69, v248
	v_mov_b32_e32 v70, v248
	v_mov_b32_e32 v71, v248
	v_mov_b32_e32 v72, v248
	v_mov_b32_e32 v73, v248
	v_mov_b32_e32 v74, v248
	v_mov_b32_e32 v75, v248
	v_mov_b32_e32 v76, v248
	v_mov_b32_e32 v77, v248
	v_mov_b32_e32 v78, v248
	v_mov_b32_e32 v79, v248
	s_waitcnt vmcnt(11)
	ds_write_b128 v246, v[12:15]
	s_waitcnt vmcnt(10)
	ds_write_b128 v247, v[16:19]
	s_waitcnt vmcnt(9)
	ds_write_b128 v32, v[20:23]
	s_waitcnt vmcnt(8)
	ds_write_b128 v245, v[24:27] offset:53248
	s_waitcnt vmcnt(7)
	ds_write_b128 v245, v[28:31] offset:57344
	v_mov_b32_e32 v14, v1
	v_mov_b32_e32 v15, v1
	v_mov_b32_e32 v12, v1
	v_mov_b32_e32 v13, v1
	v_mov_b64_e32 v[46:47], v[14:15]
	v_mov_b64_e32 v[30:31], v[14:15]
	v_mov_b64_e32 v[62:63], v[14:15]
	v_mov_b64_e32 v[44:45], v[12:13]
	v_mov_b64_e32 v[42:43], v[10:11]
	v_mov_b64_e32 v[40:41], v[8:9]
	v_mov_b64_e32 v[38:39], v[6:7]
	v_mov_b64_e32 v[36:37], v[4:5]
	v_mov_b64_e32 v[34:35], v[2:3]
	v_mov_b64_e32 v[32:33], v[0:1]
	v_mov_b64_e32 v[28:29], v[12:13]
	v_mov_b64_e32 v[26:27], v[10:11]
	v_mov_b64_e32 v[24:25], v[8:9]
	v_mov_b64_e32 v[22:23], v[6:7]
	v_mov_b64_e32 v[20:21], v[4:5]
	v_mov_b64_e32 v[18:19], v[2:3]
	v_mov_b64_e32 v[16:17], v[0:1]
	v_mov_b64_e32 v[60:61], v[12:13]
	v_mov_b64_e32 v[58:59], v[10:11]
	v_mov_b64_e32 v[56:57], v[8:9]
	v_mov_b64_e32 v[54:55], v[6:7]
	v_mov_b64_e32 v[52:53], v[4:5]
	v_mov_b64_e32 v[50:51], v[2:3]
	v_mov_b64_e32 v[48:49], v[0:1]
	v_mov_b32_e32 v48, 0
	v_mov_b32_e32 v49, 0
	v_mov_b32_e32 v50, 0
	v_mov_b32_e32 v51, 0
	v_mov_b32_e32 v52, 0
	v_mov_b32_e32 v53, 0
	v_mov_b32_e32 v54, 0
	v_mov_b32_e32 v55, 0
	s_waitcnt lgkmcnt(0)
	s_barrier
	s_branch .LBB0_137
; __device__ __forceinline__ int crow(int r, int hi) { return (r & 3) + 8 * (r >> 2) + 4 * hi; }
; template <int DK>
; __device__ __forceinline__ void attn_unit(LAS unsigned char* lds, const GAS bf16* Qp, const GAS bf16* Kp, const GAS bf16* Vp, GAS bf16* Yp, int b, int j, int nkeys, int tid, int lane, int wave) {
;     ...
;         if (t == 0 || __any(rm > 8.0f)) {
;             const float dl = (t == 0) ? rm : fmaxf(rm, 0.f), f = __builtin_amdgcn_exp2f(-dl);
;             mhat += dl;
; #pragma unroll
;             for (int r = 0; r < 16; ++r) { p[0][r] -= dl; p[1][r] -= dl; p[2][r] -= dl; p[3][r] -= dl; negm[r] = -mhat; }
;             if (hi == 0) wsf[r32] = f;
;             asm volatile("s_waitcnt lgkmcnt(0)" ::: "memory");
; #pragma unroll
;             for (int r = 0; r < 16; ++r) { const float fr = wsf[crow(r, hi)]; o0[r] *= fr; o1[r] *= fr; ol[r] *= fr; }
;             asm volatile("s_waitcnt lgkmcnt(0)" ::: "memory");
.LBB0_135:
	s_or_b64 exec, exec, s[50:51]
	v_add_f32_e32 v248, v248, v0
	v_pk_add_f32 v[128:129], v[128:129], v[0:1] op_sel_hi:[1,0] neg_lo:[0,1] neg_hi:[0,1]
	v_pk_add_f32 v[112:113], v[112:113], v[0:1] op_sel_hi:[1,0] neg_lo:[0,1] neg_hi:[0,1]
	v_pk_add_f32 v[96:97], v[96:97], v[0:1] op_sel_hi:[1,0] neg_lo:[0,1] neg_hi:[0,1]
	v_pk_add_f32 v[80:81], v[80:81], v[0:1] op_sel_hi:[1,0] neg_lo:[0,1] neg_hi:[0,1]
	v_pk_add_f32 v[130:131], v[130:131], v[0:1] op_sel_hi:[1,0] neg_lo:[0,1] neg_hi:[0,1]
	v_pk_add_f32 v[114:115], v[114:115], v[0:1] op_sel_hi:[1,0] neg_lo:[0,1] neg_hi:[0,1]
	v_pk_add_f32 v[98:99], v[98:99], v[0:1] op_sel_hi:[1,0] neg_lo:[0,1] neg_hi:[0,1]
	v_pk_add_f32 v[82:83], v[82:83], v[0:1] op_sel_hi:[1,0] neg_lo:[0,1] neg_hi:[0,1]
	v_pk_add_f32 v[132:133], v[132:133], v[0:1] op_sel_hi:[1,0] neg_lo:[0,1] neg_hi:[0,1]
	v_pk_add_f32 v[116:117], v[116:117], v[0:1] op_sel_hi:[1,0] neg_lo:[0,1] neg_hi:[0,1]
	v_pk_add_f32 v[100:101], v[100:101], v[0:1] op_sel_hi:[1,0] neg_lo:[0,1] neg_hi:[0,1]
	v_pk_add_f32 v[84:85], v[84:85], v[0:1] op_sel_hi:[1,0] neg_lo:[0,1] neg_hi:[0,1]
	v_pk_add_f32 v[134:135], v[134:135], v[0:1] op_sel_hi:[1,0] neg_lo:[0,1] neg_hi:[0,1]
	v_pk_add_f32 v[118:119], v[118:119], v[0:1] op_sel_hi:[1,0] neg_lo:[0,1] neg_hi:[0,1]
	v_pk_add_f32 v[102:103], v[102:103], v[0:1] op_sel_hi:[1,0] neg_lo:[0,1] neg_hi:[0,1]
	v_pk_add_f32 v[86:87], v[86:87], v[0:1] op_sel_hi:[1,0] neg_lo:[0,1] neg_hi:[0,1]
	v_pk_add_f32 v[136:137], v[136:137], v[0:1] op_sel_hi:[1,0] neg_lo:[0,1] neg_hi:[0,1]
	v_pk_add_f32 v[120:121], v[120:121], v[0:1] op_sel_hi:[1,0] neg_lo:[0,1] neg_hi:[0,1]
	v_pk_add_f32 v[104:105], v[104:105], v[0:1] op_sel_hi:[1,0] neg_lo:[0,1] neg_hi:[0,1]
	v_pk_add_f32 v[88:89], v[88:89], v[0:1] op_sel_hi:[1,0] neg_lo:[0,1] neg_hi:[0,1]
	v_pk_add_f32 v[138:139], v[138:139], v[0:1] op_sel_hi:[1,0] neg_lo:[0,1] neg_hi:[0,1]
	v_pk_add_f32 v[122:123], v[122:123], v[0:1] op_sel_hi:[1,0] neg_lo:[0,1] neg_hi:[0,1]
	v_pk_add_f32 v[106:107], v[106:107], v[0:1] op_sel_hi:[1,0] neg_lo:[0,1] neg_hi:[0,1]
	v_pk_add_f32 v[90:91], v[90:91], v[0:1] op_sel_hi:[1,0] neg_lo:[0,1] neg_hi:[0,1]
	v_pk_add_f32 v[140:141], v[140:141], v[0:1] op_sel_hi:[1,0] neg_lo:[0,1] neg_hi:[0,1]
	v_pk_add_f32 v[124:125], v[124:125], v[0:1] op_sel_hi:[1,0] neg_lo:[0,1] neg_hi:[0,1]
	v_pk_add_f32 v[108:109], v[108:109], v[0:1] op_sel_hi:[1,0] neg_lo:[0,1] neg_hi:[0,1]
	v_pk_add_f32 v[92:93], v[92:93], v[0:1] op_sel_hi:[1,0] neg_lo:[0,1] neg_hi:[0,1]
	v_pk_add_f32 v[142:143], v[142:143], v[0:1] op_sel_hi:[1,0] neg_lo:[0,1] neg_hi:[0,1]
	v_pk_add_f32 v[126:127], v[126:127], v[0:1] op_sel_hi:[1,0] neg_lo:[0,1] neg_hi:[0,1]
	v_pk_add_f32 v[110:111], v[110:111], v[0:1] op_sel_hi:[1,0] neg_lo:[0,1] neg_hi:[0,1]
	v_pk_add_f32 v[94:95], v[94:95], v[0:1] op_sel_hi:[1,0] neg_lo:[0,1] neg_hi:[0,1]
	s_waitcnt lgkmcnt(0)
	v_add_u32_e32 v0, s63, v236
	ds_read_b128 v[2:5], v0
	ds_read_b128 v[6:9], v0 offset:32
	ds_read_b128 v[10:13], v0 offset:64
	ds_read_b128 v[64:67], v0 offset:96
	s_waitcnt lgkmcnt(0)
	v_xor_b32_e32 v79, 0x80000000, v248
	s_waitcnt lgkmcnt(2)
	v_pk_mul_f32 v[36:37], v[36:37], v[6:7]
	s_waitcnt lgkmcnt(1)
	v_pk_mul_f32 v[40:41], v[40:41], v[10:11]
	s_waitcnt lgkmcnt(0)
	v_pk_mul_f32 v[44:45], v[44:45], v[64:65]
	v_pk_mul_f32 v[46:47], v[46:47], v[66:67]
	v_pk_mul_f32 v[42:43], v[42:43], v[12:13]
	v_pk_mul_f32 v[38:39], v[38:39], v[8:9]
	v_pk_mul_f32 v[34:35], v[34:35], v[4:5]
	v_pk_mul_f32 v[32:33], v[32:33], v[2:3]
	v_pk_mul_f32 v[28:29], v[28:29], v[64:65]
	v_pk_mul_f32 v[24:25], v[24:25], v[10:11]
	v_pk_mul_f32 v[20:21], v[20:21], v[6:7]
	v_pk_mul_f32 v[30:31], v[30:31], v[66:67]
	v_pk_mul_f32 v[26:27], v[26:27], v[12:13]
	v_pk_mul_f32 v[22:23], v[22:23], v[8:9]
	v_pk_mul_f32 v[18:19], v[18:19], v[4:5]
	v_pk_mul_f32 v[16:17], v[16:17], v[2:3]
	v_pk_mul_f32 v[52:53], v[52:53], v[56:57] op_sel_hi:[1,0]
	v_pk_mul_f32 v[54:55], v[54:55], v[56:57] op_sel_hi:[1,0]
	v_pk_mul_f32 v[50:51], v[50:51], v[56:57] op_sel_hi:[1,0]
	v_pk_mul_f32 v[48:49], v[48:49], v[56:57] op_sel_hi:[1,0]
	v_mov_b32_e32 v78, v79
	v_mov_b32_e32 v77, v79
	v_mov_b32_e32 v76, v79
	v_mov_b32_e32 v75, v79
	v_mov_b32_e32 v74, v79
	v_mov_b32_e32 v73, v79
	v_mov_b32_e32 v72, v79
	v_mov_b32_e32 v71, v79
	v_mov_b32_e32 v70, v79
	v_mov_b32_e32 v69, v79
	v_mov_b32_e32 v68, v79
	v_mov_b32_e32 v67, v79
	v_mov_b32_e32 v66, v79
	v_mov_b32_e32 v65, v79
	v_mov_b32_e32 v64, v79
; #define LAS __attribute__((address_space(3)))
; #define AT_PVK(ks, VF) do { o0 = __builtin_amdgcn_mfma_f32_32x32x16_bf16(__builtin_bit_cast(bf16x8, pw[ks]), VF[0], o0, 0, 0, 0); \
;             o1 = __builtin_amdgcn_mfma_f32_32x32x16_bf16(__builtin_bit_cast(bf16x8, pw[ks]), VF[1], o1, 0, 0, 0); \
;             ol = __builtin_amdgcn_mfma_f32_32x32x16_bf16(__builtin_bit_cast(bf16x8, pw[ks]), ones, ol, 0, 0, 0); } while (0)
; template <int DK>
; __device__ __forceinline__ void attn_unit(LAS unsigned char* lds, const GAS bf16* Qp, const GAS bf16* Kp, const GAS bf16* Vp, GAS bf16* Yp, int b, int j, int nkeys, int tid, int lane, int wave) {
;     ...
;         u32x4 pw[8];
;         { LAS unsigned char* vb = lds + cur * AT_VBUF + vfo;
;     ...
;           bf16x8 vfa[2], vfb[2];
;           vfa[0] = AT_VF(0, 0); vfa[1] = AT_VF(1, 0);
;           AT_EXPQ(0);
;           __builtin_amdgcn_sched_barrier(0);
; #pragma unroll
;           for (int q4 = 0; q4 < 4; ++q4) {
;               vfb[0] = AT_VF(0, 2 * q4 + 1); vfb[1] = AT_VF(1, 2 * q4 + 1);
;               AT_PVK(2 * q4, vfa);
;               if (q4 + 1 < 4) { AT_EXPQ(q4 + 1); vfa[0] = AT_VF(0, 2 * q4 + 2); vfa[1] = AT_VF(1, 2 * q4 + 2); }
;               AT_PVK(2 * q4 + 1, vfb);
;               __builtin_amdgcn_sched_barrier(0);
;           }
.LBB0_136:
	v_lshl_add_u32 v0, s11, 14, v243
	ds_read_b64_tr_b16 v[2:3], v0 offset:53248
	ds_read_b64_tr_b16 v[4:5], v0 offset:53760
	ds_read_b64_tr_b16 v[6:7], v0 offset:61440
	ds_read_b64_tr_b16 v[8:9], v0 offset:61952
	v_exp_f32_e32 v10, v128
	v_exp_f32_e32 v11, v129
	v_exp_f32_e32 v12, v130
	v_exp_f32_e32 v13, v131
	v_exp_f32_e32 v15, v132
	v_exp_f32_e32 v128, v133
	v_exp_f32_e32 v129, v134
	v_exp_f32_e32 v130, v135
	v_exp_f32_e32 v131, v136
	v_exp_f32_e32 v132, v137
	v_exp_f32_e32 v133, v138
	v_exp_f32_e32 v134, v139
	v_exp_f32_e32 v135, v140
	v_exp_f32_e32 v136, v141
	v_exp_f32_e32 v137, v142
	v_exp_f32_e32 v138, v143
	v_add_u32_e32 v14, 0xd000, v0
	v_pk_add_f32 v[48:49], v[48:49], v[10:11]
	v_pk_add_f32 v[50:51], v[50:51], v[12:13]
	v_add_f32_e32 v52, v52, v15
	v_add_f32_e32 v53, v53, v128
	v_add_f32_e32 v54, v54, v129
	v_add_f32_e32 v55, v55, v130
	v_add_f32_e32 v48, v48, v131
	v_add_f32_e32 v49, v49, v132
	v_add_f32_e32 v50, v50, v133
	v_add_f32_e32 v51, v51, v134
	v_add_f32_e32 v52, v52, v135
	v_add_f32_e32 v53, v53, v136
	v_add_f32_e32 v54, v54, v137
	v_add_f32_e32 v55, v55, v138
	v_cvt_pk_bf16_f32 v10, v10, v11
	v_cvt_pk_bf16_f32 v11, v12, v13
	v_cvt_pk_bf16_f32 v12, v15, v128
	v_cvt_pk_bf16_f32 v13, v129, v130
	v_cvt_pk_bf16_f32 v128, v131, v132
	v_cvt_pk_bf16_f32 v129, v133, v134
	v_cvt_pk_bf16_f32 v130, v135, v136
	v_cvt_pk_bf16_f32 v131, v137, v138
	s_mov_b32 s69, s68
	s_waitcnt lgkmcnt(2)
	v_mfma_f32_32x32x16_bf16 v[32:47], v[10:13], v[2:5], v[32:47]
	s_mov_b32 s70, s68
	s_mov_b32 s71, s68
	v_mov_b64_e32 v[2:3], s[68:69]
	v_mov_b64_e32 v[4:5], s[70:71]
	v_exp_f32_e32 v15, v124
	ds_read_b64_tr_b16 v[132:133], v0 offset:54272
	ds_read_b64_tr_b16 v[134:135], v0 offset:54784
	s_waitcnt lgkmcnt(2)
	v_mfma_f32_32x32x16_bf16 v[16:31], v[10:13], v[6:9], v[16:31]
	v_exp_f32_e32 v6, v120
	v_exp_f32_e32 v7, v121
	v_exp_f32_e32 v8, v122
	v_exp_f32_e32 v9, v123
	v_exp_f32_e32 v120, v125
	v_exp_f32_e32 v121, v126
	v_pk_add_f32 v[48:49], v[48:49], v[6:7]
	v_cvt_pk_bf16_f32 v6, v6, v7
	s_nop 0
	v_exp_f32_e32 v10, v127
	v_pk_add_f32 v[50:51], v[50:51], v[8:9]
	v_add_f32_e32 v52, v52, v15
	v_add_f32_e32 v53, v53, v120
	v_cvt_pk_bf16_f32 v7, v8, v9
	v_cvt_pk_bf16_f32 v8, v15, v120
	v_exp_f32_e32 v15, v112
	v_add_f32_e32 v54, v54, v121
	v_add_f32_e32 v55, v55, v10
	v_cvt_pk_bf16_f32 v9, v121, v10
	ds_read_b64_tr_b16 v[10:11], v0 offset:55296
	ds_read_b64_tr_b16 v[12:13], v0 offset:55808
	ds_read_b64_tr_b16 v[120:121], v0 offset:62464
	ds_read_b64_tr_b16 v[122:123], v0 offset:62976
	ds_read_b64_tr_b16 v[124:125], v0 offset:63488
	ds_read_b64_tr_b16 v[126:127], v0 offset:64000
	s_waitcnt lgkmcnt(6)
	v_mfma_f32_32x32x16_bf16 v[32:47], v[128:131], v[132:135], v[32:47]
	v_exp_f32_e32 v112, v113
	v_exp_f32_e32 v113, v114
	v_exp_f32_e32 v114, v115
	v_exp_f32_e32 v115, v116
	v_exp_f32_e32 v116, v117
	v_exp_f32_e32 v117, v118
	v_exp_f32_e32 v118, v119
	s_waitcnt lgkmcnt(2)
	v_mfma_f32_32x32x16_bf16 v[16:31], v[128:131], v[120:123], v[16:31]
	v_add_f32_e32 v48, v48, v15
	v_add_f32_e32 v49, v49, v112
	v_add_f32_e32 v50, v50, v113
	v_add_f32_e32 v51, v51, v114
	v_add_f32_e32 v52, v52, v115
	v_add_f32_e32 v53, v53, v116
	v_add_f32_e32 v54, v54, v117
	v_add_f32_e32 v55, v55, v118
	v_cvt_pk_bf16_f32 v112, v15, v112
	v_cvt_pk_bf16_f32 v113, v113, v114
	v_cvt_pk_bf16_f32 v114, v115, v116
	v_cvt_pk_bf16_f32 v115, v117, v118
	s_nop 0
	s_nop 0
	v_mfma_f32_32x32x16_bf16 v[32:47], v[112:115], v[10:13], v[32:47]
	ds_read_b64_tr_b16 v[10:11], v0 offset:56320
	ds_read_b64_tr_b16 v[12:13], v0 offset:56832
	v_exp_f32_e32 v15, v104
	v_exp_f32_e32 v104, v105
	v_exp_f32_e32 v105, v106
	v_exp_f32_e32 v106, v107
	v_exp_f32_e32 v107, v108
	v_exp_f32_e32 v108, v109
	s_waitcnt lgkmcnt(2)
; #define AT_PVK(ks, VF) do { o0 = __builtin_amdgcn_mfma_f32_32x32x16_bf16(__builtin_bit_cast(bf16x8, pw[ks]), VF[0], o0, 0, 0, 0); \
;             o1 = __builtin_amdgcn_mfma_f32_32x32x16_bf16(__builtin_bit_cast(bf16x8, pw[ks]), VF[1], o1, 0, 0, 0); \
;             ol = __builtin_amdgcn_mfma_f32_32x32x16_bf16(__builtin_bit_cast(bf16x8, pw[ks]), ones, ol, 0, 0, 0); } while (0)
; template <int DK>
; __device__ __forceinline__ void attn_unit(LAS unsigned char* lds, const GAS bf16* Qp, const GAS bf16* Kp, const GAS bf16* Vp, GAS bf16* Yp, int b, int j, int nkeys, int tid, int lane, int wave) {
;     ...
; #pragma unroll
;           for (int q4 = 0; q4 < 4; ++q4) {
;               vfb[0] = AT_VF(0, 2 * q4 + 1); vfb[1] = AT_VF(1, 2 * q4 + 1);
;               AT_PVK(2 * q4, vfa);
;               if (q4 + 1 < 4) { AT_EXPQ(q4 + 1); vfa[0] = AT_VF(0, 2 * q4 + 2); vfa[1] = AT_VF(1, 2 * q4 + 2); }
;               AT_PVK(2 * q4 + 1, vfb);
;               __builtin_amdgcn_sched_barrier(0);
;           }
;     ...
;         }
;         __syncthreads();
	v_mfma_f32_32x32x16_bf16 v[16:31], v[112:115], v[124:127], v[16:31]
	v_exp_f32_e32 v109, v110
	v_exp_f32_e32 v110, v111
	v_add_f32_e32 v48, v48, v105
	v_add_f32_e32 v49, v49, v106
	v_add_f32_e32 v50, v50, v107
	v_add_f32_e32 v51, v51, v108
	v_add_f32_e32 v52, v52, v15
	v_add_f32_e32 v53, v53, v104
	v_add_f32_e32 v54, v54, v109
	v_add_f32_e32 v55, v55, v110
	v_cvt_pk_bf16_f32 v105, v105, v106
	v_cvt_pk_bf16_f32 v106, v107, v108
	v_cvt_pk_bf16_f32 v104, v15, v104
	v_cvt_pk_bf16_f32 v107, v109, v110
	ds_read_b64_tr_b16 v[108:109], v0 offset:57344
	ds_read_b64_tr_b16 v[110:111], v0 offset:57856
	s_nop 0
	v_exp_f32_e32 v15, v96
	v_exp_f32_e32 v96, v97
	v_exp_f32_e32 v97, v98
	v_exp_f32_e32 v98, v99
	v_exp_f32_e32 v99, v100
	v_exp_f32_e32 v100, v103
	s_waitcnt lgkmcnt(2)
	v_mfma_f32_32x32x16_bf16 v[32:47], v[6:9], v[10:13], v[32:47]
	ds_read_b64_tr_b16 v[10:11], v0 offset:64512
	ds_read_b64_tr_b16 v[12:13], v0 offset:65024
	ds_read_b64_tr_b16 v[112:113], v14 offset:12288
	ds_read_b64_tr_b16 v[114:115], v14 offset:12800
	s_waitcnt lgkmcnt(2)
	v_mfma_f32_32x32x16_bf16 v[16:31], v[6:9], v[10:13], v[16:31]
	v_exp_f32_e32 v12, v101
	v_exp_f32_e32 v13, v102
	v_add_f32_e32 v48, v48, v15
	v_add_f32_e32 v49, v49, v96
	v_add_f32_e32 v50, v50, v97
	v_add_f32_e32 v51, v51, v98
	v_add_f32_e32 v52, v52, v99
	v_add_f32_e32 v53, v53, v12
	v_add_f32_e32 v54, v54, v13
	v_add_f32_e32 v55, v55, v100
	v_cvt_pk_bf16_f32 v10, v15, v96
	v_cvt_pk_bf16_f32 v11, v97, v98
	v_cvt_pk_bf16_f32 v12, v99, v12
	v_cvt_pk_bf16_f32 v13, v13, v100
	s_nop 0
	s_nop 0
	v_mfma_f32_32x32x16_bf16 v[32:47], v[10:13], v[108:111], v[32:47]
	ds_read_b64_tr_b16 v[6:7], v0 offset:58368
	ds_read_b64_tr_b16 v[8:9], v0 offset:58880
	v_exp_f32_e32 v15, v88
	v_exp_f32_e32 v88, v89
	v_exp_f32_e32 v89, v90
	v_exp_f32_e32 v90, v91
	v_exp_f32_e32 v91, v92
	v_exp_f32_e32 v92, v93
	s_waitcnt lgkmcnt(2)
	v_mfma_f32_32x32x16_bf16 v[16:31], v[10:13], v[112:115], v[16:31]
	v_exp_f32_e32 v93, v94
	s_nop 0
	v_exp_f32_e32 v13, v95
	v_add_f32_e32 v48, v48, v15
	v_add_f32_e32 v49, v49, v88
	v_add_f32_e32 v50, v50, v89
	v_add_f32_e32 v51, v51, v90
	v_add_f32_e32 v52, v52, v91
	v_add_f32_e32 v53, v53, v92
	v_add_f32_e32 v54, v54, v93
	v_add_f32_e32 v55, v55, v13
	v_cvt_pk_bf16_f32 v10, v15, v88
	v_cvt_pk_bf16_f32 v11, v89, v90
	v_cvt_pk_bf16_f32 v12, v91, v92
	v_cvt_pk_bf16_f32 v13, v93, v13
	ds_read_b64_tr_b16 v[88:89], v0 offset:59392
	ds_read_b64_tr_b16 v[90:91], v0 offset:59904
	v_exp_f32_e32 v15, v80
	s_waitcnt lgkmcnt(2)
	v_mfma_f32_32x32x16_bf16 v[32:47], v[104:107], v[6:9], v[32:47]
	ds_read_b64_tr_b16 v[6:7], v14 offset:13312
	ds_read_b64_tr_b16 v[8:9], v14 offset:13824
	ds_read_b64_tr_b16 v[92:93], v14 offset:14336
	ds_read_b64_tr_b16 v[94:95], v14 offset:14848
	v_exp_f32_e32 v80, v81
	v_exp_f32_e32 v81, v82
	v_exp_f32_e32 v82, v83
	v_exp_f32_e32 v83, v84
	v_exp_f32_e32 v84, v87
	s_waitcnt lgkmcnt(2)
	v_mfma_f32_32x32x16_bf16 v[16:31], v[104:107], v[6:9], v[16:31]
	v_exp_f32_e32 v8, v85
	v_exp_f32_e32 v9, v86
	v_add_f32_e32 v48, v48, v15
	v_add_f32_e32 v49, v49, v80
	v_add_f32_e32 v50, v50, v81
	v_add_f32_e32 v51, v51, v82
	v_add_f32_e32 v52, v52, v83
	v_add_f32_e32 v53, v53, v8
	v_add_f32_e32 v54, v54, v9
	v_add_f32_e32 v55, v55, v84
	v_cvt_pk_bf16_f32 v6, v15, v80
	v_cvt_pk_bf16_f32 v7, v81, v82
	v_cvt_pk_bf16_f32 v8, v83, v8
	v_cvt_pk_bf16_f32 v9, v9, v84
	s_nop 0
	s_nop 0
	v_mfma_f32_32x32x16_bf16 v[32:47], v[6:9], v[88:91], v[32:47]
	s_waitcnt lgkmcnt(0)
	v_mfma_f32_32x32x16_bf16 v[16:31], v[6:9], v[92:95], v[16:31]
	s_nop 0
	ds_read_b64_tr_b16 v[6:7], v0 offset:60416
	ds_read_b64_tr_b16 v[8:9], v0 offset:60928
	ds_read_b64_tr_b16 v[80:81], v14 offset:15360
	ds_read_b64_tr_b16 v[82:83], v14 offset:15872
	s_waitcnt lgkmcnt(2)
	v_mfma_f32_32x32x16_bf16 v[32:47], v[10:13], v[6:9], v[32:47]
	s_waitcnt lgkmcnt(0)
	v_mfma_f32_32x32x16_bf16 v[16:31], v[10:13], v[80:83], v[16:31]
	s_nop 0
	s_add_i32 s10, s10, 1
	s_add_u32 s48, s48, 0x4000
	s_addc_u32 s49, s49, 0
	s_add_u32 s46, s46, 0x6000
	s_addc_u32 s47, s47, 0
	s_add_i32 s11, s9, s10
	s_cmp_lg_u32 s11, 2
	s_barrier
	s_cbranch_scc0 .LBB0_150

; template <int DK>
; __device__ __forceinline__ void attn_unit(LAS unsigned char* lds, const GAS bf16* Qp, const GAS bf16* Kp, const GAS bf16* Vp, GAS bf16* Yp, int b, int j, int nkeys, int tid, int lane, int wave) {
;     ...
;         if (t == 0 || __any(rm > 8.0f)) {
;             const float dl = (t == 0) ? rm : fmaxf(rm, 0.f), f = __builtin_amdgcn_exp2f(-dl);
;             mhat += dl;
; #pragma unroll
;             for (int r = 0; r < 16; ++r) { p[0][r] -= dl; p[1][r] -= dl; p[2][r] -= dl; p[3][r] -= dl; negm[r] = -mhat; }
;             if (hi == 0) wsf[r32] = f;
.LBB0_146:
	s_andn2_b64 vcc, exec, s[50:51]
	s_cbranch_vccnz .LBB0_136
	v_exp_f32_e64 v56, -v0
	s_and_saveexec_b64 s[50:51], s[40:41]
	s_cbranch_execz .LBB0_135
	v_exp_f32_e64 v2, -v0
	ds_write_b32 v238, v2
	s_branch .LBB0_135

; #define GAS __attribute__((address_space(1)))
; __device__ __forceinline__ unsigned f2bf(float f) { unsigned u = __builtin_bit_cast(unsigned, f); return (u + 0x7fffu + ((u >> 16) & 1u)) >> 16; }
; __device__ __forceinline__ int crow(int r, int hi) { return (r & 3) + 8 * (r >> 2) + 4 * hi; }
; template <int DK>
; __device__ __forceinline__ void attn_unit(LAS unsigned char* lds, const GAS bf16* Qp, const GAS bf16* Kp, const GAS bf16* Vp, GAS bf16* Yp, int b, int j, int nkeys, int tid, int lane, int wave) {
;     ...
;     const int pos0 = 256 * j + wave * 32;
; #pragma unroll
;     for (int r = 0; r < 16; ++r) {
;         const int qq = crow(r, hi); const float inv = __builtin_amdgcn_rcpf(ol[r]); const int pos = pos0 + qq;
;         const int row = (j == 0) ? MLAT + b * CTXL + pos : b * SEQ + pos - CTXL;
;         GAS bf16* yp = Yp + (size_t)row * DM + r32;
;         yp[0] = (bf16)f2bf(o0[r] * inv); yp[32] = (bf16)f2bf(o1[r] * inv);
;     }
.LBB0_150:
	v_pk_add_f32 v[48:49], v[48:49], v[50:51]
	v_pk_add_f32 v[52:53], v[52:53], v[54:55]
	v_pk_add_f32 v[48:49], v[48:49], v[52:53]
	v_add_f32_e32 v48, v48, v49
	v_mov_b32_e32 v49, v48
	s_nop 1
	v_permlane32_swap_b32_e32 v48, v49
	v_add_f32_e32 v48, v48, v49
	v_add_u32_e32 v0, s63, v236
	ds_write_b32 v238, v48
	s_waitcnt lgkmcnt(0)
	ds_read_b128 v[48:51], v0
	ds_read_b128 v[52:55], v0 offset:32
	ds_read_b128 v[56:59], v0 offset:64
	ds_read_b128 v[60:63], v0 offset:96
	s_waitcnt lgkmcnt(0)
	s_lshl_b32 s8, s74, 6
	s_ashr_i32 s9, s8, 31
	v_lshl_add_u64 v[2:3], s[8:9], 1, v[204:205]
	s_lshl_b32 s8, s73, 11
	s_add_i32 s10, s8, 0xffffff00
	s_lshl_b32 s8, s73, 8
	s_add_i32 s11, s8, 0x4000
	s_and_b64 s[8:9], s[44:45], exec
	v_rcp_f32_e32 v0, v48
	s_cselect_b32 s8, s11, s10
	s_add_i32 s8, s8, s7
	v_add_u32_e32 v4, s8, v239
	v_ashrrev_i32_e32 v5, 31, v4
	v_lshlrev_b64 v[6:7], 11, v[4:5]
	v_mul_f32_e32 v5, v32, v0
	v_bfe_u32 v8, v5, 16, 1
	v_lshl_add_u64 v[6:7], v[2:3], 0, v[6:7]
	v_add3_u32 v5, v5, v8, s3
	v_mul_f32_e32 v0, v16, v0
	global_store_short_d16_hi v[6:7], v5, off offset:1280
	v_bfe_u32 v5, v0, 16, 1
	v_add3_u32 v0, v0, v5, s3
	global_store_short_d16_hi v[6:7], v0, off offset:1344
	v_rcp_f32_e32 v0, v49
	v_or_b32_e32 v6, 1, v4
	v_ashrrev_i32_e32 v7, 31, v6
	v_lshlrev_b64 v[6:7], 11, v[6:7]
	v_mul_f32_e32 v5, v33, v0
	v_bfe_u32 v8, v5, 16, 1
	v_lshl_add_u64 v[6:7], v[2:3], 0, v[6:7]
	v_add3_u32 v5, v5, v8, s3
	v_mul_f32_e32 v0, v17, v0
	global_store_short_d16_hi v[6:7], v5, off offset:1280
	v_bfe_u32 v5, v0, 16, 1
	v_add3_u32 v0, v0, v5, s3
	global_store_short_d16_hi v[6:7], v0, off offset:1344
	v_rcp_f32_e32 v0, v50
	v_or_b32_e32 v6, 2, v4
	v_ashrrev_i32_e32 v7, 31, v6
	v_lshlrev_b64 v[6:7], 11, v[6:7]
	v_mul_f32_e32 v5, v34, v0
	v_bfe_u32 v8, v5, 16, 1
	v_lshl_add_u64 v[6:7], v[2:3], 0, v[6:7]
	v_add3_u32 v5, v5, v8, s3
	v_mul_f32_e32 v0, v18, v0
	global_store_short_d16_hi v[6:7], v5, off offset:1280
	v_bfe_u32 v5, v0, 16, 1
	v_add3_u32 v0, v0, v5, s3
	global_store_short_d16_hi v[6:7], v0, off offset:1344
	v_rcp_f32_e32 v0, v51
	v_or_b32_e32 v6, 3, v4
	v_ashrrev_i32_e32 v7, 31, v6
	v_lshlrev_b64 v[6:7], 11, v[6:7]
	v_mul_f32_e32 v5, v35, v0
	v_bfe_u32 v8, v5, 16, 1
	v_lshl_add_u64 v[6:7], v[2:3], 0, v[6:7]
	v_add3_u32 v5, v5, v8, s3
	v_mul_f32_e32 v0, v19, v0
	global_store_short_d16_hi v[6:7], v5, off offset:1280
	v_bfe_u32 v5, v0, 16, 1
	v_add3_u32 v0, v0, v5, s3
	global_store_short_d16_hi v[6:7], v0, off offset:1344
	v_rcp_f32_e32 v0, v52
	v_add_u32_e32 v6, 8, v4
	v_ashrrev_i32_e32 v7, 31, v6
	v_lshlrev_b64 v[6:7], 11, v[6:7]
	v_mul_f32_e32 v5, v36, v0
	v_bfe_u32 v8, v5, 16, 1
	v_lshl_add_u64 v[6:7], v[2:3], 0, v[6:7]
	v_add3_u32 v5, v5, v8, s3
	v_mul_f32_e32 v0, v20, v0
	global_store_short_d16_hi v[6:7], v5, off offset:1280
	v_bfe_u32 v5, v0, 16, 1
	v_add3_u32 v0, v0, v5, s3
	global_store_short_d16_hi v[6:7], v0, off offset:1344
	v_rcp_f32_e32 v0, v53
	v_add_u32_e32 v6, 9, v4
	v_ashrrev_i32_e32 v7, 31, v6
	v_lshlrev_b64 v[6:7], 11, v[6:7]
	v_mul_f32_e32 v5, v37, v0
	v_bfe_u32 v8, v5, 16, 1
	v_lshl_add_u64 v[6:7], v[2:3], 0, v[6:7]
	v_add3_u32 v5, v5, v8, s3
	v_mul_f32_e32 v0, v21, v0
	global_store_short_d16_hi v[6:7], v5, off offset:1280
	v_bfe_u32 v5, v0, 16, 1
	v_add3_u32 v0, v0, v5, s3
	global_store_short_d16_hi v[6:7], v0, off offset:1344
	v_rcp_f32_e32 v0, v54
	v_add_u32_e32 v6, 10, v4
	v_ashrrev_i32_e32 v7, 31, v6
	v_lshlrev_b64 v[6:7], 11, v[6:7]
	v_mul_f32_e32 v5, v38, v0
	v_bfe_u32 v8, v5, 16, 1
	v_lshl_add_u64 v[6:7], v[2:3], 0, v[6:7]
	v_add3_u32 v5, v5, v8, s3
	v_mul_f32_e32 v0, v22, v0
	global_store_short_d16_hi v[6:7], v5, off offset:1280
	v_bfe_u32 v5, v0, 16, 1
	v_add3_u32 v0, v0, v5, s3
	global_store_short_d16_hi v[6:7], v0, off offset:1344
	v_rcp_f32_e32 v0, v55
	v_add_u32_e32 v6, 11, v4
	v_ashrrev_i32_e32 v7, 31, v6
; #define GAS __attribute__((address_space(1)))
; __device__ __forceinline__ unsigned f2bf(float f) { unsigned u = __builtin_bit_cast(unsigned, f); return (u + 0x7fffu + ((u >> 16) & 1u)) >> 16; }
; __device__ __forceinline__ int crow(int r, int hi) { return (r & 3) + 8 * (r >> 2) + 4 * hi; }
; template <int DK>
; __device__ __forceinline__ void attn_unit(LAS unsigned char* lds, const GAS bf16* Qp, const GAS bf16* Kp, const GAS bf16* Vp, GAS bf16* Yp, int b, int j, int nkeys, int tid, int lane, int wave) {
;     ...
;     const int pos0 = 256 * j + wave * 32;
; #pragma unroll
;     for (int r = 0; r < 16; ++r) {
;         const int qq = crow(r, hi); const float inv = __builtin_amdgcn_rcpf(ol[r]); const int pos = pos0 + qq;
;         const int row = (j == 0) ? MLAT + b * CTXL + pos : b * SEQ + pos - CTXL;
;         GAS bf16* yp = Yp + (size_t)row * DM + r32;
;         yp[0] = (bf16)f2bf(o0[r] * inv); yp[32] = (bf16)f2bf(o1[r] * inv);
;     }
	v_lshlrev_b64 v[6:7], 11, v[6:7]
	v_mul_f32_e32 v5, v39, v0
	v_bfe_u32 v8, v5, 16, 1
	v_lshl_add_u64 v[6:7], v[2:3], 0, v[6:7]
	v_add3_u32 v5, v5, v8, s3
	v_mul_f32_e32 v0, v23, v0
	global_store_short_d16_hi v[6:7], v5, off offset:1280
	v_bfe_u32 v5, v0, 16, 1
	v_add3_u32 v0, v0, v5, s3
	global_store_short_d16_hi v[6:7], v0, off offset:1344
	v_rcp_f32_e32 v0, v56
	v_add_u32_e32 v6, 16, v4
	v_ashrrev_i32_e32 v7, 31, v6
	v_lshlrev_b64 v[6:7], 11, v[6:7]
	v_mul_f32_e32 v5, v40, v0
	v_bfe_u32 v8, v5, 16, 1
	v_lshl_add_u64 v[6:7], v[2:3], 0, v[6:7]
	v_add3_u32 v5, v5, v8, s3
	v_mul_f32_e32 v0, v24, v0
	global_store_short_d16_hi v[6:7], v5, off offset:1280
	v_bfe_u32 v5, v0, 16, 1
	v_add3_u32 v0, v0, v5, s3
	global_store_short_d16_hi v[6:7], v0, off offset:1344
	v_rcp_f32_e32 v0, v57
	v_add_u32_e32 v6, 17, v4
	v_ashrrev_i32_e32 v7, 31, v6
	v_lshlrev_b64 v[6:7], 11, v[6:7]
	v_mul_f32_e32 v5, v41, v0
	v_bfe_u32 v8, v5, 16, 1
	v_lshl_add_u64 v[6:7], v[2:3], 0, v[6:7]
	v_add3_u32 v5, v5, v8, s3
	v_mul_f32_e32 v0, v25, v0
	global_store_short_d16_hi v[6:7], v5, off offset:1280
	v_bfe_u32 v5, v0, 16, 1
	v_add3_u32 v0, v0, v5, s3
	global_store_short_d16_hi v[6:7], v0, off offset:1344
	v_rcp_f32_e32 v0, v58
	v_add_u32_e32 v6, 18, v4
	v_ashrrev_i32_e32 v7, 31, v6
	v_lshlrev_b64 v[6:7], 11, v[6:7]
	v_mul_f32_e32 v5, v42, v0
	v_bfe_u32 v8, v5, 16, 1
	v_lshl_add_u64 v[6:7], v[2:3], 0, v[6:7]
	v_add3_u32 v5, v5, v8, s3
	v_mul_f32_e32 v0, v26, v0
	global_store_short_d16_hi v[6:7], v5, off offset:1280
	v_bfe_u32 v5, v0, 16, 1
	v_add3_u32 v0, v0, v5, s3
	global_store_short_d16_hi v[6:7], v0, off offset:1344
	v_rcp_f32_e32 v0, v59
	v_add_u32_e32 v6, 19, v4
	v_ashrrev_i32_e32 v7, 31, v6
	v_lshlrev_b64 v[6:7], 11, v[6:7]
	v_mul_f32_e32 v5, v43, v0
	v_bfe_u32 v8, v5, 16, 1
	v_lshl_add_u64 v[6:7], v[2:3], 0, v[6:7]
	v_add3_u32 v5, v5, v8, s3
	v_mul_f32_e32 v0, v27, v0
	global_store_short_d16_hi v[6:7], v5, off offset:1280
	v_bfe_u32 v5, v0, 16, 1
	v_add3_u32 v0, v0, v5, s3
	global_store_short_d16_hi v[6:7], v0, off offset:1344
	v_rcp_f32_e32 v0, v60
	v_add_u32_e32 v6, 24, v4
	v_ashrrev_i32_e32 v7, 31, v6
	v_lshlrev_b64 v[6:7], 11, v[6:7]
	v_mul_f32_e32 v5, v44, v0
	v_bfe_u32 v8, v5, 16, 1
	v_lshl_add_u64 v[6:7], v[2:3], 0, v[6:7]
	v_add3_u32 v5, v5, v8, s3
	v_mul_f32_e32 v0, v28, v0
	global_store_short_d16_hi v[6:7], v5, off offset:1280
	v_bfe_u32 v5, v0, 16, 1
	v_add3_u32 v0, v0, v5, s3
	global_store_short_d16_hi v[6:7], v0, off offset:1344
	v_rcp_f32_e32 v0, v61
	v_add_u32_e32 v6, 25, v4
	v_ashrrev_i32_e32 v7, 31, v6
	v_lshlrev_b64 v[6:7], 11, v[6:7]
	v_mul_f32_e32 v5, v45, v0
	v_bfe_u32 v8, v5, 16, 1
	v_lshl_add_u64 v[6:7], v[2:3], 0, v[6:7]
	v_add3_u32 v5, v5, v8, s3
	v_mul_f32_e32 v0, v29, v0
	global_store_short_d16_hi v[6:7], v5, off offset:1280
	v_bfe_u32 v5, v0, 16, 1
	v_add3_u32 v0, v0, v5, s3
	global_store_short_d16_hi v[6:7], v0, off offset:1344
	v_rcp_f32_e32 v0, v62
	v_add_u32_e32 v6, 26, v4
	v_ashrrev_i32_e32 v7, 31, v6
	v_lshlrev_b64 v[6:7], 11, v[6:7]
	v_mul_f32_e32 v5, v46, v0
	v_bfe_u32 v8, v5, 16, 1
	v_lshl_add_u64 v[6:7], v[2:3], 0, v[6:7]
	v_add3_u32 v5, v5, v8, s3
	v_mul_f32_e32 v0, v30, v0
	global_store_short_d16_hi v[6:7], v5, off offset:1280
	v_bfe_u32 v5, v0, 16, 1
	v_add3_u32 v0, v0, v5, s3
	global_store_short_d16_hi v[6:7], v0, off offset:1344
	v_rcp_f32_e32 v0, v63
	v_add_u32_e32 v4, 27, v4
	v_ashrrev_i32_e32 v5, 31, v4
	v_lshlrev_b64 v[4:5], 11, v[4:5]
	v_lshl_add_u64 v[2:3], v[2:3], 0, v[4:5]
	v_mul_f32_e32 v4, v47, v0
	v_bfe_u32 v5, v4, 16, 1
	v_add3_u32 v4, v4, v5, s3
	v_mul_f32_e32 v0, v31, v0
	global_store_short_d16_hi v[2:3], v4, off offset:1280
	v_bfe_u32 v4, v0, 16, 1
	v_add3_u32 v0, v0, v4, s3
	global_store_short_d16_hi v[2:3], v0, off offset:1344
	s_waitcnt lgkmcnt(0)
	s_barrier
	s_mov_b32 s7, 1
	s_branch .LBB0_167

; #define LAS __attribute__((address_space(3)))
; __device__ __forceinline__ int crow(int r, int hi) { return (r & 3) + 8 * (r >> 2) + 4 * hi; }
; template <int DK>
; __device__ __forceinline__ void attn_unit(LAS unsigned char* lds, const GAS bf16* Qp, const GAS bf16* Kp, const GAS bf16* Vp, GAS bf16* Yp, int b, int j, int nkeys, int tid, int lane, int wave) {
;     ...
;         { LAS unsigned char* kb = lds + cur * AT_KBUF + kfo;
;           bf16x8 ka[2][4];
; #pragma unroll
;           for (int q4 = 0; q4 < 4; ++q4) ka[0][q4] = *(LAS bf16x8*)(kb + q4 * 32 * KSTR);
; #pragma unroll
;           for (int d0 = 0; d0 < ND; ++d0) {
;               if (d0 + 1 < ND) {
; #pragma unroll
;                   for (int q4 = 0; q4 < 4; ++q4) ka[(d0 + 1) & 1][q4] = *(LAS bf16x8*)(kb + q4 * 32 * KSTR + (d0 + 1) * 32);
;               }
; #pragma unroll
;               for (int q4 = 0; q4 < 4; ++q4) p[q4] = __builtin_amdgcn_mfma_f32_32x32x16_bf16(ka[d0 & 1][q4], qr[d0], d0 == 0 ? negm : p[q4], 0, 0, 0);
;               if (d0 == 0) { if (t + 1 < NT) AT_STORE(cur ^ 1); if (t + 2 < NT) AT_LOAD(t + 2); }
;               __builtin_amdgcn_sched_barrier(0);
;           } }
;         float rma = fmaxf(p[0][0], p[1][0]), rmb = fmaxf(p[2][0], p[3][0]);
; #pragma unroll
;         for (int r = 1; r < 16; ++r) { rma = fmaxf(fmaxf(rma, p[0][r]), p[1][r]); rmb = fmaxf(fmaxf(rmb, p[2][r]), p[3][r]); }
;         float rm = fmaxf(rma, rmb);
;         { const unsigned ru_ = __builtin_bit_cast(unsigned, rm); auto rr_ = __builtin_amdgcn_permlane32_swap(ru_, ru_, false, false);
;           rm = fmaxf(__builtin_bit_cast(float, (unsigned)rr_[0]), __builtin_bit_cast(float, (unsigned)rr_[1])); }
;         if (t == 0 || __any(rm > 8.0f)) {
;             const float dl = (t == 0) ? rm : fmaxf(rm, 0.f), f = __builtin_amdgcn_exp2f(-dl);
;             mhat += dl;
; #pragma unroll
;             for (int r = 0; r < 16; ++r) { p[0][r] -= dl; p[1][r] -= dl; p[2][r] -= dl; p[3][r] -= dl; negm[r] = -mhat; }
;             if (hi == 0) wsf[r32] = f;
;             asm volatile("s_waitcnt lgkmcnt(0)" ::: "memory");
; #pragma unroll
;             for (int r = 0; r < 16; ++r) { const float fr = wsf[crow(r, hi)]; o0[r] *= fr; o1[r] *= fr; ol[r] *= fr; }
.LBB0_154:
	s_waitcnt lgkmcnt(7)
	v_mfma_f32_32x32x16_bf16 v[2:17], v[80:83], v[134:137], v[2:17]
	s_waitcnt lgkmcnt(6)
	v_mfma_f32_32x32x16_bf16 v[18:33], v[76:79], v[134:137], v[18:33]
	s_waitcnt lgkmcnt(5)
	v_mfma_f32_32x32x16_bf16 v[34:49], v[72:75], v[134:137], v[34:49]
	ds_read_b128 v[72:75], v242 offset:64
	ds_read_b128 v[76:79], v242 offset:4672
	ds_read_b128 v[80:83], v242 offset:9280
	ds_read_b128 v[84:87], v242 offset:13888
	s_waitcnt lgkmcnt(8)
	v_mfma_f32_32x32x16_bf16 v[52:67], v[68:71], v[134:137], v[52:67]
	s_waitcnt lgkmcnt(3)
	v_mfma_f32_32x32x16_bf16 v[2:17], v[72:75], v[138:141], v[2:17]
	s_waitcnt lgkmcnt(2)
	v_mfma_f32_32x32x16_bf16 v[18:33], v[76:79], v[138:141], v[18:33]
	s_waitcnt lgkmcnt(1)
	v_mfma_f32_32x32x16_bf16 v[34:49], v[80:83], v[138:141], v[34:49]
	ds_read_b128 v[68:71], v242 offset:96
	ds_read_b128 v[72:75], v242 offset:4704
	ds_read_b128 v[76:79], v242 offset:9312
	ds_read_b128 v[80:83], v242 offset:13920
	s_waitcnt lgkmcnt(4)
	v_mfma_f32_32x32x16_bf16 v[52:67], v[84:87], v[138:141], v[52:67]
	s_waitcnt lgkmcnt(3)
	v_mfma_f32_32x32x16_bf16 v[2:17], v[68:71], v[142:145], v[2:17]
	s_waitcnt lgkmcnt(2)
	v_mfma_f32_32x32x16_bf16 v[18:33], v[72:75], v[142:145], v[18:33]
	s_waitcnt lgkmcnt(1)
	v_mfma_f32_32x32x16_bf16 v[34:49], v[76:79], v[142:145], v[34:49]
	s_waitcnt lgkmcnt(0)
	v_mfma_f32_32x32x16_bf16 v[52:67], v[80:83], v[142:145], v[52:67]
	s_nop 11
	v_max_f32_e32 v0, v52, v52
	v_max_f32_e32 v50, v34, v34
	v_max_f32_e32 v0, v50, v0
	v_max3_f32 v50, v2, v18, v3
	v_max3_f32 v0, v0, v35, v53
	v_max3_f32 v50, v50, v19, v4
	v_max3_f32 v0, v0, v36, v54
	v_max3_f32 v50, v50, v20, v5
	v_max3_f32 v0, v0, v37, v55
	v_max3_f32 v50, v50, v21, v6
	v_max3_f32 v0, v0, v38, v56
	v_max3_f32 v50, v50, v22, v7
	v_max3_f32 v0, v0, v39, v57
	v_max3_f32 v50, v50, v23, v8
	v_max3_f32 v0, v0, v40, v58
	v_max3_f32 v50, v50, v24, v9
	v_max3_f32 v0, v0, v41, v59
	v_max3_f32 v50, v50, v25, v10
	v_max3_f32 v0, v0, v42, v60
	v_max3_f32 v50, v50, v26, v11
	v_max3_f32 v0, v0, v43, v61
	v_max3_f32 v50, v50, v27, v12
	v_max3_f32 v0, v0, v44, v62
	v_max3_f32 v50, v50, v28, v13
	v_max3_f32 v0, v0, v45, v63
	v_max3_f32 v50, v50, v29, v14
	v_max3_f32 v0, v0, v46, v64
	v_max3_f32 v50, v50, v30, v15
	v_max3_f32 v0, v0, v47, v65
	v_max3_f32 v50, v50, v31, v16
	v_max3_f32 v0, v0, v48, v66
	v_max3_f32 v50, v50, v32, v17
	v_max3_f32 v0, v0, v49, v67
	v_max3_f32 v0, v50, v33, v0
	v_mov_b32_e32 v50, v0
	s_nop 1
	v_permlane32_swap_b32_e32 v0, v50
	v_max_f32_e32 v50, v50, v50
	v_max_f32_e32 v0, v0, v0
	v_max_f32_e32 v0, v0, v50
	s_and_saveexec_b64 s[22:23], s[40:41]
	v_exp_f32_e64 v50, -v0
	ds_write_b32 v238, v50
	s_or_b64 exec, exec, s[22:23]
	s_waitcnt lgkmcnt(0)
	v_add_u32_e32 v185, s63, v236
	v_sub_f32_e32 v51, v2, v0
	v_sub_f32_e32 v76, v18, v0
	v_sub_f32_e32 v78, v52, v0
	v_sub_f32_e32 v52, v3, v0
	v_sub_f32_e32 v79, v19, v0
	v_sub_f32_e32 v81, v53, v0
	v_sub_f32_e32 v53, v4, v0
	v_sub_f32_e32 v82, v20, v0
	v_sub_f32_e32 v84, v54, v0
	v_sub_f32_e32 v54, v5, v0
	v_sub_f32_e32 v85, v21, v0
	v_sub_f32_e32 v87, v55, v0
	v_sub_f32_e32 v55, v6, v0
	v_sub_f32_e32 v88, v22, v0
	v_sub_f32_e32 v89, v38, v0
	v_sub_f32_e32 v38, v7, v0
	v_sub_f32_e32 v91, v23, v0
	v_sub_f32_e32 v92, v39, v0
	v_sub_f32_e32 v39, v8, v0
	v_sub_f32_e32 v94, v24, v0
	v_sub_f32_e32 v95, v40, v0
	v_sub_f32_e32 v40, v9, v0
	v_sub_f32_e32 v97, v25, v0
	ds_read_b128 v[2:5], v185 offset:64
	ds_read_b128 v[6:9], v185 offset:96
	ds_read_b128 v[18:21], v185
	ds_read_b128 v[22:25], v185 offset:32
	s_waitcnt lgkmcnt(0)
	v_sub_f32_e32 v77, v34, v0
	v_sub_f32_e32 v80, v35, v0
	v_sub_f32_e32 v83, v36, v0
	v_sub_f32_e32 v86, v37, v0
	v_sub_f32_e32 v90, v56, v0
	v_sub_f32_e32 v93, v57, v0
	v_sub_f32_e32 v96, v58, v0
	v_sub_f32_e32 v99, v59, v0
	ds_read_b64_tr_b16 v[34:35], v243 offset:53248
	ds_read_b64_tr_b16 v[36:37], v243 offset:53760
	ds_read_b64_tr_b16 v[56:57], v243 offset:61440
	ds_read_b64_tr_b16 v[58:59], v243 offset:61952
	v_sub_f32_e32 v98, v41, v0
	v_sub_f32_e32 v41, v10, v0
	v_sub_f32_e32 v72, v26, v0
	v_sub_f32_e32 v26, v11, v0
	v_sub_f32_e32 v73, v27, v0
	v_sub_f32_e32 v27, v12, v0
	v_sub_f32_e32 v74, v28, v0
	v_sub_f32_e32 v28, v13, v0
	v_sub_f32_e32 v75, v29, v0
	v_sub_f32_e32 v29, v14, v0
	v_sub_f32_e32 v108, v30, v0
	v_sub_f32_e32 v30, v15, v0
	v_sub_f32_e32 v111, v31, v0
	v_sub_f32_e32 v31, v16, v0
	v_sub_f32_e32 v114, v32, v0
	v_sub_f32_e32 v32, v17, v0
	v_sub_f32_e32 v117, v33, v0
	s_waitcnt lgkmcnt(6)
	v_pk_mul_f32 v[16:17], v[8:9], 0 op_sel_hi:[1,0]
	v_pk_mul_f32 v[12:13], v[4:5], 0 op_sel_hi:[1,0]
	s_waitcnt lgkmcnt(4)
	v_pk_mul_f32 v[8:9], v[24:25], 0 op_sel_hi:[1,0]
	v_pk_mul_f32 v[4:5], v[20:21], 0 op_sel_hi:[1,0]
	v_pk_mul_f32 v[14:15], v[6:7], 0 op_sel_hi:[1,0]
	v_pk_mul_f32 v[10:11], v[2:3], 0 op_sel_hi:[1,0]
	v_pk_mul_f32 v[6:7], v[22:23], 0 op_sel_hi:[1,0]
	v_pk_mul_f32 v[2:3], v[18:19], 0 op_sel_hi:[1,0]
	v_exp_f32_e32 v18, v51
	v_exp_f32_e32 v19, v52
	v_exp_f32_e32 v20, v53
	v_exp_f32_e32 v21, v54
	v_exp_f32_e32 v22, v55
	v_exp_f32_e32 v23, v38
	v_exp_f32_e32 v24, v39
	v_exp_f32_e32 v25, v40
	v_exp_f32_e32 v33, v41
	v_exp_f32_e32 v26, v26
	v_exp_f32_e32 v27, v27
	v_exp_f32_e32 v28, v28
	v_exp_f32_e32 v29, v29
	v_exp_f32_e32 v30, v30
	v_exp_f32_e32 v31, v31
	v_exp_f32_e32 v32, v32
	v_add_f32_e32 v184, 0, v0
	v_xor_b32_e32 v50, 0x80000000, v184
	v_sub_f32_e32 v101, v60, v0
	v_sub_f32_e32 v103, v61, v0
	v_sub_f32_e32 v105, v62, v0
	v_sub_f32_e32 v107, v63, v0
	v_sub_f32_e32 v110, v64, v0
	v_sub_f32_e32 v113, v65, v0
	s_lshr_b32 s4, s4, 7
	v_cvt_pk_bf16_f32 v60, v18, v19
	v_cvt_pk_bf16_f32 v61, v20, v21
	v_cvt_pk_bf16_f32 v62, v22, v23
	v_cvt_pk_bf16_f32 v63, v24, v25
	v_cvt_pk_bf16_f32 v64, v33, v26
	v_cvt_pk_bf16_f32 v65, v27, v28
	v_sub_f32_e32 v100, v42, v0
	v_sub_f32_e32 v102, v43, v0
	v_sub_f32_e32 v104, v44, v0
	v_sub_f32_e32 v106, v45, v0
	v_sub_f32_e32 v109, v46, v0
	v_sub_f32_e32 v112, v47, v0
	v_sub_f32_e32 v115, v48, v0
	v_sub_f32_e32 v116, v66, v0
	v_sub_f32_e32 v118, v49, v0
	v_sub_f32_e32 v0, v67, v0
	v_cvt_pk_bf16_f32 v66, v29, v30
	v_cvt_pk_bf16_f32 v67, v31, v32
	s_waitcnt lgkmcnt(2)
; #define LAS __attribute__((address_space(3)))
; #define AT_PVK(ks, VF) do { o0 = __builtin_amdgcn_mfma_f32_32x32x16_bf16(__builtin_bit_cast(bf16x8, pw[ks]), VF[0], o0, 0, 0, 0); \
;             o1 = __builtin_amdgcn_mfma_f32_32x32x16_bf16(__builtin_bit_cast(bf16x8, pw[ks]), VF[1], o1, 0, 0, 0); \
;             ol = __builtin_amdgcn_mfma_f32_32x32x16_bf16(__builtin_bit_cast(bf16x8, pw[ks]), ones, ol, 0, 0, 0); } while (0)
; template <int DK>
; __device__ __forceinline__ void attn_unit(LAS unsigned char* lds, const GAS bf16* Qp, const GAS bf16* Kp, const GAS bf16* Vp, GAS bf16* Yp, int b, int j, int nkeys, int tid, int lane, int wave) {
;     ...
;         u32x4 pw[8];
;         { LAS unsigned char* vb = lds + cur * AT_VBUF + vfo;
;     ...
;           bf16x8 vfa[2], vfb[2];
;           vfa[0] = AT_VF(0, 0); vfa[1] = AT_VF(1, 0);
;           AT_EXPQ(0);
;           __builtin_amdgcn_sched_barrier(0);
; #pragma unroll
;           for (int q4 = 0; q4 < 4; ++q4) {
;               vfb[0] = AT_VF(0, 2 * q4 + 1); vfb[1] = AT_VF(1, 2 * q4 + 1);
;               AT_PVK(2 * q4, vfa);
;               if (q4 + 1 < 4) { AT_EXPQ(q4 + 1); vfa[0] = AT_VF(0, 2 * q4 + 2); vfa[1] = AT_VF(1, 2 * q4 + 2); }
;               AT_PVK(2 * q4 + 1, vfb);
;               __builtin_amdgcn_sched_barrier(0);
;           }
	v_mfma_f32_32x32x16_bf16 v[18:33], v[60:63], v[34:37], v[2:17]
	s_mov_b32 s69, s68
	s_mov_b32 s70, s68
	s_mov_b32 s71, s68
	v_mov_b64_e32 v[52:53], s[68:69]
	v_mov_b64_e32 v[54:55], s[70:71]
	ds_read_b64_tr_b16 v[68:69], v243 offset:54272
	ds_read_b64_tr_b16 v[70:71], v243 offset:54784
	v_exp_f32_e32 v51, v72
	s_waitcnt lgkmcnt(2)
	v_mfma_f32_32x32x16_bf16 v[34:49], v[60:63], v[56:59], v[2:17]
	v_exp_f32_e32 v56, v73
	v_exp_f32_e32 v57, v74
	v_exp_f32_e32 v58, v75
	v_exp_f32_e32 v59, v108
	v_exp_f32_e32 v72, v111
	v_exp_f32_e32 v73, v114
	v_cvt_pk_bf16_f32 v57, v57, v58
	v_mfma_f32_32x32x16_bf16 v[2:17], v[60:63], v[52:55], v[2:17]
	v_exp_f32_e32 v60, v117
	v_cvt_pk_bf16_f32 v58, v59, v72
	v_cvt_pk_bf16_f32 v56, v51, v56
	v_exp_f32_e32 v51, v76
	v_cvt_pk_bf16_f32 v59, v73, v60
	ds_read_b64_tr_b16 v[60:61], v243 offset:55296
	ds_read_b64_tr_b16 v[62:63], v243 offset:55808
	v_exp_f32_e32 v76, v79
	s_waitcnt lgkmcnt(2)
	v_mfma_f32_32x32x16_bf16 v[18:33], v[64:67], v[68:71], v[18:33]
	ds_read_b64_tr_b16 v[68:69], v243 offset:62464
	ds_read_b64_tr_b16 v[70:71], v243 offset:62976
	ds_read_b64_tr_b16 v[72:73], v243 offset:63488
	ds_read_b64_tr_b16 v[74:75], v243 offset:64000
	v_exp_f32_e32 v79, v82
	v_exp_f32_e32 v82, v85
	v_exp_f32_e32 v85, v88
	v_exp_f32_e32 v88, v97
	s_waitcnt lgkmcnt(2)
	v_mfma_f32_32x32x16_bf16 v[34:49], v[64:67], v[68:71], v[34:49]
	v_exp_f32_e32 v70, v91
	v_exp_f32_e32 v71, v94
	v_cvt_pk_bf16_f32 v68, v51, v76
	v_cvt_pk_bf16_f32 v69, v79, v82
	v_cvt_pk_bf16_f32 v70, v85, v70
	v_cvt_pk_bf16_f32 v71, v71, v88
	v_mfma_f32_32x32x16_bf16 v[2:17], v[64:67], v[52:55], v[2:17]
	s_nop 0
	v_mfma_f32_32x32x16_bf16 v[18:33], v[68:71], v[60:63], v[18:33]
	ds_read_b64_tr_b16 v[60:61], v243 offset:56320
	ds_read_b64_tr_b16 v[62:63], v243 offset:56832
	v_exp_f32_e32 v65, v104
	v_exp_f32_e32 v66, v106
	v_exp_f32_e32 v67, v109
	v_exp_f32_e32 v51, v100
	v_exp_f32_e32 v64, v102
	v_cvt_pk_bf16_f32 v65, v65, v66
	s_waitcnt lgkmcnt(2)
	v_mfma_f32_32x32x16_bf16 v[34:49], v[68:71], v[72:75], v[34:49]
	v_exp_f32_e32 v72, v112
	v_exp_f32_e32 v73, v115
	v_cvt_pk_bf16_f32 v64, v51, v64
	v_exp_f32_e32 v51, v77
	v_cvt_pk_bf16_f32 v66, v67, v72
	v_exp_f32_e32 v76, v80
	v_exp_f32_e32 v77, v83
	v_mfma_f32_32x32x16_bf16 v[2:17], v[68:71], v[52:55], v[2:17]
	v_exp_f32_e32 v68, v118
	v_exp_f32_e32 v79, v86
	v_exp_f32_e32 v80, v89
	v_exp_f32_e32 v82, v98
	v_cvt_pk_bf16_f32 v67, v73, v68
	ds_read_b64_tr_b16 v[68:69], v243 offset:57344
	ds_read_b64_tr_b16 v[70:71], v243 offset:57856
	s_waitcnt lgkmcnt(2)
	v_mfma_f32_32x32x16_bf16 v[18:33], v[56:59], v[60:63], v[18:33]
	ds_read_b64_tr_b16 v[60:61], v243 offset:64512
	ds_read_b64_tr_b16 v[62:63], v243 offset:65024
	ds_read_b64_tr_b16 v[72:73], v244 offset:12288
	ds_read_b64_tr_b16 v[74:75], v244 offset:12800
	s_waitcnt lgkmcnt(2)
	v_mfma_f32_32x32x16_bf16 v[34:49], v[56:59], v[60:63], v[34:49]
	v_exp_f32_e32 v62, v92
	v_exp_f32_e32 v63, v95
	v_cvt_pk_bf16_f32 v60, v51, v76
	v_cvt_pk_bf16_f32 v61, v77, v79
	v_cvt_pk_bf16_f32 v62, v80, v62
	v_cvt_pk_bf16_f32 v63, v63, v82
	v_mfma_f32_32x32x16_bf16 v[2:17], v[56:59], v[52:55], v[2:17]
	s_nop 0
	v_mfma_f32_32x32x16_bf16 v[18:33], v[60:63], v[68:71], v[18:33]
	ds_read_b64_tr_b16 v[56:57], v243 offset:58368
	ds_read_b64_tr_b16 v[58:59], v243 offset:58880
	v_exp_f32_e32 v51, v101
	v_exp_f32_e32 v68, v103
	v_exp_f32_e32 v69, v105
	v_exp_f32_e32 v70, v107
	v_exp_f32_e32 v71, v110
	v_exp_f32_e32 v0, v0
	s_waitcnt lgkmcnt(2)
	v_mfma_f32_32x32x16_bf16 v[34:49], v[60:63], v[72:75], v[34:49]
	v_exp_f32_e32 v72, v113
	v_exp_f32_e32 v73, v116
	v_exp_f32_e32 v76, v84
	v_exp_f32_e32 v77, v87
	v_exp_f32_e32 v79, v99
	v_mfma_f32_32x32x16_bf16 v[2:17], v[60:63], v[52:55], v[2:17]
	v_cvt_pk_bf16_f32 v60, v51, v68
	v_cvt_pk_bf16_f32 v61, v69, v70
	v_cvt_pk_bf16_f32 v62, v71, v72
	v_cvt_pk_bf16_f32 v63, v73, v0
	ds_read_b64_tr_b16 v[68:69], v243 offset:59392
	ds_read_b64_tr_b16 v[70:71], v243 offset:59904
	v_exp_f32_e32 v0, v78
	v_exp_f32_e32 v51, v81
	s_waitcnt lgkmcnt(2)
	v_mfma_f32_32x32x16_bf16 v[18:33], v[64:67], v[56:59], v[18:33]
	ds_read_b64_tr_b16 v[56:57], v244 offset:13312
	ds_read_b64_tr_b16 v[58:59], v244 offset:13824
	ds_read_b64_tr_b16 v[72:73], v244 offset:14336
	ds_read_b64_tr_b16 v[74:75], v244 offset:14848
	v_exp_f32_e32 v78, v90
	s_waitcnt lgkmcnt(2)
	v_mfma_f32_32x32x16_bf16 v[34:49], v[64:67], v[56:59], v[34:49]
	v_exp_f32_e32 v58, v93
	v_exp_f32_e32 v59, v96
	v_cvt_pk_bf16_f32 v56, v0, v51
	v_cvt_pk_bf16_f32 v57, v76, v77
	v_cvt_pk_bf16_f32 v58, v78, v58
	v_cvt_pk_bf16_f32 v59, v59, v79
	v_mfma_f32_32x32x16_bf16 v[2:17], v[64:67], v[52:55], v[2:17]
	s_nop 0
	v_mfma_f32_32x32x16_bf16 v[18:33], v[56:59], v[68:71], v[18:33]
	s_waitcnt lgkmcnt(0)
	v_mfma_f32_32x32x16_bf16 v[34:49], v[56:59], v[72:75], v[34:49]
	v_mfma_f32_32x32x16_bf16 v[2:17], v[56:59], v[52:55], v[2:17]
	ds_read_b64_tr_b16 v[56:57], v243 offset:60416
	ds_read_b64_tr_b16 v[58:59], v243 offset:60928
	ds_read_b64_tr_b16 v[64:65], v244 offset:15360
	ds_read_b64_tr_b16 v[66:67], v244 offset:15872
	s_waitcnt lgkmcnt(2)
	v_mfma_f32_32x32x16_bf16 v[18:33], v[60:63], v[56:59], v[18:33]
	s_waitcnt lgkmcnt(0)
	v_mfma_f32_32x32x16_bf16 v[34:49], v[60:63], v[64:67], v[34:49]
	v_mfma_f32_32x32x16_bf16 v[2:17], v[60:63], v[52:55], v[2:17]
	v_mad_i64_i32 v[180:181], s[8:9], s6, v213, v[208:209]
	v_mad_i64_i32 v[182:183], s[6:7], s6, v213, v[210:211]
	s_lshl_b32 s6, s4, 14
	s_add_u32 s6, s6, 0xffffc000
	s_mov_b64 s[22:23], 0
	s_mov_b32 s7, 3
	v_mov_b32_e32 v51, v50
	v_mov_b32_e32 v52, v50
	v_mov_b32_e32 v53, v50
	v_mov_b32_e32 v54, v50
	v_mov_b32_e32 v55, v50
	v_mov_b32_e32 v56, v50
	v_mov_b32_e32 v57, v50
	v_mov_b32_e32 v58, v50
	v_mov_b32_e32 v59, v50
	v_mov_b32_e32 v60, v50
	v_mov_b32_e32 v61, v50
	v_mov_b32_e32 v62, v50
	v_mov_b32_e32 v63, v50
	v_mov_b32_e32 v64, v50
	v_mov_b32_e32 v65, v50
	v_add_u32_e32 v66, s63, v236
	ds_write_b32 v66, v2
	ds_write_b32 v66, v3 offset:4
	ds_write_b32 v66, v4 offset:8
	ds_write_b32 v66, v5 offset:12
	ds_write_b32 v66, v6 offset:32
	ds_write_b32 v66, v7 offset:36
	ds_write_b32 v66, v8 offset:40
	ds_write_b32 v66, v9 offset:44
	ds_write_b32 v66, v10 offset:64
	ds_write_b32 v66, v11 offset:68
	ds_write_b32 v66, v12 offset:72
	ds_write_b32 v66, v13 offset:76
	ds_write_b32 v66, v14 offset:96
	ds_write_b32 v66, v15 offset:100
	ds_write_b32 v66, v16 offset:104
	ds_write_b32 v66, v17 offset:108
	s_waitcnt lgkmcnt(0)
	ds_read_b32 v67, v238
	v_mov_b32_e32 v2, 0
	v_mov_b32_e32 v3, 0
	v_mov_b32_e32 v4, 0
	v_mov_b32_e32 v5, 0
	v_mov_b32_e32 v6, 0
	v_mov_b32_e32 v7, 0
	v_mov_b32_e32 v8, 0
	v_mov_b32_e32 v9, 0
	s_waitcnt lgkmcnt(0)
	s_and_saveexec_b64 s[46:47], s[40:41]
	v_mov_b32_e32 v2, v67
	s_or_b64 exec, exec, s[46:47]
	s_barrier
	s_branch .LBB0_159
; __device__ __forceinline__ int crow(int r, int hi) { return (r & 3) + 8 * (r >> 2) + 4 * hi; }
; template <int DK>
; __device__ __forceinline__ void attn_unit(LAS unsigned char* lds, const GAS bf16* Qp, const GAS bf16* Kp, const GAS bf16* Vp, GAS bf16* Yp, int b, int j, int nkeys, int tid, int lane, int wave) {
;     ...
;         if (t == 0 || __any(rm > 8.0f)) {
;             const float dl = (t == 0) ? rm : fmaxf(rm, 0.f), f = __builtin_amdgcn_exp2f(-dl);
;             mhat += dl;
; #pragma unroll
;             for (int r = 0; r < 16; ++r) { p[0][r] -= dl; p[1][r] -= dl; p[2][r] -= dl; p[3][r] -= dl; negm[r] = -mhat; }
;             if (hi == 0) wsf[r32] = f;
;             asm volatile("s_waitcnt lgkmcnt(0)" ::: "memory");
; #pragma unroll
;             for (int r = 0; r < 16; ++r) { const float fr = wsf[crow(r, hi)]; o0[r] *= fr; o1[r] *= fr; ol[r] *= fr; }
;             asm volatile("s_waitcnt lgkmcnt(0)" ::: "memory");
.LBB0_157:
	s_or_b64 exec, exec, s[46:47]
	s_waitcnt lgkmcnt(0)
	ds_read_b128 v[50:53], v185
	ds_read_b128 v[54:57], v185 offset:32
	ds_read_b128 v[58:61], v185 offset:64
	ds_read_b128 v[162:165], v185 offset:96
	v_add_f32_e32 v184, v184, v0
	s_waitcnt lgkmcnt(0)
	v_xor_b32_e32 v65, 0x80000000, v184
	v_pk_add_f32 v[114:115], v[114:115], v[0:1] op_sel_hi:[1,0] neg_lo:[0,1] neg_hi:[0,1]
	v_pk_add_f32 v[98:99], v[98:99], v[0:1] op_sel_hi:[1,0] neg_lo:[0,1] neg_hi:[0,1]
	v_pk_add_f32 v[82:83], v[82:83], v[0:1] op_sel_hi:[1,0] neg_lo:[0,1] neg_hi:[0,1]
	v_pk_add_f32 v[66:67], v[66:67], v[0:1] op_sel_hi:[1,0] neg_lo:[0,1] neg_hi:[0,1]
	v_pk_add_f32 v[116:117], v[116:117], v[0:1] op_sel_hi:[1,0] neg_lo:[0,1] neg_hi:[0,1]
	v_pk_add_f32 v[100:101], v[100:101], v[0:1] op_sel_hi:[1,0] neg_lo:[0,1] neg_hi:[0,1]
	v_pk_add_f32 v[84:85], v[84:85], v[0:1] op_sel_hi:[1,0] neg_lo:[0,1] neg_hi:[0,1]
	v_pk_add_f32 v[68:69], v[68:69], v[0:1] op_sel_hi:[1,0] neg_lo:[0,1] neg_hi:[0,1]
	v_pk_add_f32 v[118:119], v[118:119], v[0:1] op_sel_hi:[1,0] neg_lo:[0,1] neg_hi:[0,1]
	v_pk_add_f32 v[102:103], v[102:103], v[0:1] op_sel_hi:[1,0] neg_lo:[0,1] neg_hi:[0,1]
	v_pk_add_f32 v[86:87], v[86:87], v[0:1] op_sel_hi:[1,0] neg_lo:[0,1] neg_hi:[0,1]
	v_pk_add_f32 v[70:71], v[70:71], v[0:1] op_sel_hi:[1,0] neg_lo:[0,1] neg_hi:[0,1]
	v_pk_add_f32 v[120:121], v[120:121], v[0:1] op_sel_hi:[1,0] neg_lo:[0,1] neg_hi:[0,1]
	v_pk_add_f32 v[104:105], v[104:105], v[0:1] op_sel_hi:[1,0] neg_lo:[0,1] neg_hi:[0,1]
	v_pk_add_f32 v[88:89], v[88:89], v[0:1] op_sel_hi:[1,0] neg_lo:[0,1] neg_hi:[0,1]
	v_pk_add_f32 v[72:73], v[72:73], v[0:1] op_sel_hi:[1,0] neg_lo:[0,1] neg_hi:[0,1]
	v_pk_add_f32 v[122:123], v[122:123], v[0:1] op_sel_hi:[1,0] neg_lo:[0,1] neg_hi:[0,1]
	v_pk_add_f32 v[106:107], v[106:107], v[0:1] op_sel_hi:[1,0] neg_lo:[0,1] neg_hi:[0,1]
	v_pk_add_f32 v[90:91], v[90:91], v[0:1] op_sel_hi:[1,0] neg_lo:[0,1] neg_hi:[0,1]
	v_pk_add_f32 v[74:75], v[74:75], v[0:1] op_sel_hi:[1,0] neg_lo:[0,1] neg_hi:[0,1]
	v_pk_add_f32 v[124:125], v[124:125], v[0:1] op_sel_hi:[1,0] neg_lo:[0,1] neg_hi:[0,1]
	v_pk_add_f32 v[108:109], v[108:109], v[0:1] op_sel_hi:[1,0] neg_lo:[0,1] neg_hi:[0,1]
	v_pk_add_f32 v[92:93], v[92:93], v[0:1] op_sel_hi:[1,0] neg_lo:[0,1] neg_hi:[0,1]
	v_pk_add_f32 v[76:77], v[76:77], v[0:1] op_sel_hi:[1,0] neg_lo:[0,1] neg_hi:[0,1]
	v_pk_add_f32 v[126:127], v[126:127], v[0:1] op_sel_hi:[1,0] neg_lo:[0,1] neg_hi:[0,1]
	v_pk_add_f32 v[110:111], v[110:111], v[0:1] op_sel_hi:[1,0] neg_lo:[0,1] neg_hi:[0,1]
	v_pk_add_f32 v[94:95], v[94:95], v[0:1] op_sel_hi:[1,0] neg_lo:[0,1] neg_hi:[0,1]
	v_pk_add_f32 v[78:79], v[78:79], v[0:1] op_sel_hi:[1,0] neg_lo:[0,1] neg_hi:[0,1]
	v_pk_add_f32 v[128:129], v[128:129], v[0:1] op_sel_hi:[1,0] neg_lo:[0,1] neg_hi:[0,1]
	v_pk_add_f32 v[112:113], v[112:113], v[0:1] op_sel_hi:[1,0] neg_lo:[0,1] neg_hi:[0,1]
	v_pk_add_f32 v[96:97], v[96:97], v[0:1] op_sel_hi:[1,0] neg_lo:[0,1] neg_hi:[0,1]
	v_pk_add_f32 v[80:81], v[80:81], v[0:1] op_sel_hi:[1,0] neg_lo:[0,1] neg_hi:[0,1]
	s_waitcnt lgkmcnt(0)
	v_pk_mul_f32 v[30:31], v[30:31], v[162:163]
	v_pk_mul_f32 v[26:27], v[26:27], v[58:59]
	v_pk_mul_f32 v[22:23], v[22:23], v[54:55]
	v_pk_mul_f32 v[32:33], v[32:33], v[164:165]
	v_pk_mul_f32 v[28:29], v[28:29], v[60:61]
	v_pk_mul_f32 v[24:25], v[24:25], v[56:57]
	v_pk_mul_f32 v[20:21], v[20:21], v[52:53]
	v_pk_mul_f32 v[18:19], v[18:19], v[50:51]
	v_pk_mul_f32 v[46:47], v[46:47], v[162:163]
	v_pk_mul_f32 v[42:43], v[42:43], v[58:59]
	v_pk_mul_f32 v[38:39], v[38:39], v[54:55]
	v_pk_mul_f32 v[48:49], v[48:49], v[164:165]
	v_pk_mul_f32 v[44:45], v[44:45], v[60:61]
	v_pk_mul_f32 v[40:41], v[40:41], v[56:57]
	v_pk_mul_f32 v[36:37], v[36:37], v[52:53]
	v_pk_mul_f32 v[34:35], v[34:35], v[50:51]
	v_pk_mul_f32 v[6:7], v[6:7], v[10:11] op_sel_hi:[1,0]
	v_pk_mul_f32 v[8:9], v[8:9], v[10:11] op_sel_hi:[1,0]
	v_pk_mul_f32 v[4:5], v[4:5], v[10:11] op_sel_hi:[1,0]
	v_pk_mul_f32 v[2:3], v[2:3], v[10:11] op_sel_hi:[1,0]
	v_mov_b32_e32 v64, v65
	v_mov_b32_e32 v63, v65
	v_mov_b32_e32 v62, v65
	v_mov_b32_e32 v61, v65
	v_mov_b32_e32 v60, v65
	v_mov_b32_e32 v59, v65
	v_mov_b32_e32 v58, v65
	v_mov_b32_e32 v57, v65
	v_mov_b32_e32 v56, v65
	v_mov_b32_e32 v55, v65
	v_mov_b32_e32 v54, v65
	v_mov_b32_e32 v53, v65
	v_mov_b32_e32 v52, v65
	v_mov_b32_e32 v51, v65
	v_mov_b32_e32 v50, v65
; #define LAS __attribute__((address_space(3)))
; #define AT_PVK(ks, VF) do { o0 = __builtin_amdgcn_mfma_f32_32x32x16_bf16(__builtin_bit_cast(bf16x8, pw[ks]), VF[0], o0, 0, 0, 0); \
;             o1 = __builtin_amdgcn_mfma_f32_32x32x16_bf16(__builtin_bit_cast(bf16x8, pw[ks]), VF[1], o1, 0, 0, 0); \
;             ol = __builtin_amdgcn_mfma_f32_32x32x16_bf16(__builtin_bit_cast(bf16x8, pw[ks]), ones, ol, 0, 0, 0); } while (0)
; template <int DK>
; __device__ __forceinline__ void attn_unit(LAS unsigned char* lds, const GAS bf16* Qp, const GAS bf16* Kp, const GAS bf16* Vp, GAS bf16* Yp, int b, int j, int nkeys, int tid, int lane, int wave) {
;     ...
;         u32x4 pw[8];
;         { LAS unsigned char* vb = lds + cur * AT_VBUF + vfo;
;     ...
;           bf16x8 vfa[2], vfb[2];
;           vfa[0] = AT_VF(0, 0); vfa[1] = AT_VF(1, 0);
;           AT_EXPQ(0);
;           __builtin_amdgcn_sched_barrier(0);
; #pragma unroll
;           for (int q4 = 0; q4 < 4; ++q4) {
;               vfb[0] = AT_VF(0, 2 * q4 + 1); vfb[1] = AT_VF(1, 2 * q4 + 1);
;               AT_PVK(2 * q4, vfa);
;               if (q4 + 1 < 4) { AT_EXPQ(q4 + 1); vfa[0] = AT_VF(0, 2 * q4 + 2); vfa[1] = AT_VF(1, 2 * q4 + 2); }
;               AT_PVK(2 * q4 + 1, vfb);
;               __builtin_amdgcn_sched_barrier(0);
;           }
.LBB0_158:
	v_lshl_add_u32 v0, s8, 14, v243
	ds_read_b64_tr_b16 v[162:163], v0 offset:53248
	ds_read_b64_tr_b16 v[164:165], v0 offset:53760
	ds_read_b64_tr_b16 v[166:167], v0 offset:61440
	ds_read_b64_tr_b16 v[168:169], v0 offset:61952
	v_exp_f32_e32 v114, v114
	v_exp_f32_e32 v115, v115
	v_exp_f32_e32 v116, v116
	v_exp_f32_e32 v117, v117
	v_exp_f32_e32 v171, v118
	v_exp_f32_e32 v172, v119
	v_exp_f32_e32 v173, v120
	v_exp_f32_e32 v121, v121
	v_exp_f32_e32 v122, v122
	v_exp_f32_e32 v123, v123
	v_exp_f32_e32 v124, v124
	v_exp_f32_e32 v125, v125
	v_exp_f32_e32 v126, v126
	v_exp_f32_e32 v127, v127
	v_exp_f32_e32 v128, v128
	v_exp_f32_e32 v129, v129
	v_add_u32_e32 v170, 0xd000, v0
	v_pk_add_f32 v[2:3], v[2:3], v[114:115]
	v_pk_add_f32 v[4:5], v[4:5], v[116:117]
	v_add_f32_e32 v6, v6, v171
	v_add_f32_e32 v7, v7, v172
	v_add_f32_e32 v8, v8, v173
	v_add_f32_e32 v9, v9, v121
	v_pk_add_f32 v[2:3], v[2:3], v[122:123]
	v_pk_add_f32 v[4:5], v[4:5], v[124:125]
	v_pk_add_f32 v[6:7], v[6:7], v[126:127]
	v_pk_add_f32 v[8:9], v[8:9], v[128:129]
	v_cvt_pk_bf16_f32 v118, v114, v115
	v_cvt_pk_bf16_f32 v119, v116, v117
	v_cvt_pk_bf16_f32 v120, v171, v172
	v_cvt_pk_bf16_f32 v121, v173, v121
	v_cvt_pk_bf16_f32 v122, v122, v123
	v_cvt_pk_bf16_f32 v123, v124, v125
	v_cvt_pk_bf16_f32 v124, v126, v127
	v_cvt_pk_bf16_f32 v125, v128, v129
	s_waitcnt lgkmcnt(2)
	v_mfma_f32_32x32x16_bf16 v[18:33], v[118:121], v[162:165], v[18:33]
	s_mov_b32 s70, s68
	s_mov_b32 s71, s68
	s_mov_b32 s69, s68
	v_mov_b64_e32 v[116:117], s[70:71]
	v_mov_b64_e32 v[114:115], s[68:69]
	ds_read_b64_tr_b16 v[126:127], v0 offset:54272
	ds_read_b64_tr_b16 v[128:129], v0 offset:54784
	v_exp_f32_e32 v106, v106
	s_waitcnt lgkmcnt(2)
	v_mfma_f32_32x32x16_bf16 v[34:49], v[118:121], v[166:169], v[34:49]
	v_exp_f32_e32 v107, v107
	v_exp_f32_e32 v108, v108
	v_exp_f32_e32 v109, v109
	v_exp_f32_e32 v110, v110
	v_exp_f32_e32 v111, v111
	v_exp_f32_e32 v112, v112
	v_exp_f32_e32 v113, v113
	s_nop 0
	v_pk_add_f32 v[2:3], v[2:3], v[106:107]
	v_pk_add_f32 v[4:5], v[4:5], v[108:109]
	v_pk_add_f32 v[6:7], v[6:7], v[110:111]
	v_pk_add_f32 v[8:9], v[8:9], v[112:113]
	v_cvt_pk_bf16_f32 v106, v106, v107
	v_cvt_pk_bf16_f32 v107, v108, v109
	v_cvt_pk_bf16_f32 v108, v110, v111
	v_cvt_pk_bf16_f32 v109, v112, v113
	ds_read_b64_tr_b16 v[110:111], v0 offset:55296
	ds_read_b64_tr_b16 v[112:113], v0 offset:55808
	v_exp_f32_e32 v98, v98
	v_exp_f32_e32 v99, v99
	s_waitcnt lgkmcnt(2)
	v_mfma_f32_32x32x16_bf16 v[18:33], v[122:125], v[126:129], v[18:33]
	ds_read_b64_tr_b16 v[118:119], v0 offset:62464
	ds_read_b64_tr_b16 v[120:121], v0 offset:62976
	ds_read_b64_tr_b16 v[126:127], v0 offset:63488
	ds_read_b64_tr_b16 v[128:129], v0 offset:64000
	v_exp_f32_e32 v100, v100
	v_exp_f32_e32 v101, v101
	v_exp_f32_e32 v102, v102
	v_exp_f32_e32 v103, v103
	v_exp_f32_e32 v104, v104
	v_exp_f32_e32 v105, v105
	s_waitcnt lgkmcnt(2)
	v_mfma_f32_32x32x16_bf16 v[34:49], v[122:125], v[118:121], v[34:49]
	v_pk_add_f32 v[2:3], v[2:3], v[98:99]
	v_pk_add_f32 v[4:5], v[4:5], v[100:101]
	v_pk_add_f32 v[6:7], v[6:7], v[102:103]
	v_pk_add_f32 v[8:9], v[8:9], v[104:105]
	v_cvt_pk_bf16_f32 v98, v98, v99
	v_cvt_pk_bf16_f32 v99, v100, v101
	v_cvt_pk_bf16_f32 v100, v102, v103
	v_cvt_pk_bf16_f32 v101, v104, v105
	s_nop 0
	s_nop 0
	v_mfma_f32_32x32x16_bf16 v[18:33], v[98:101], v[110:113], v[18:33]
	ds_read_b64_tr_b16 v[102:103], v0 offset:56320
	ds_read_b64_tr_b16 v[104:105], v0 offset:56832
	v_exp_f32_e32 v90, v90
	v_exp_f32_e32 v91, v91
	v_exp_f32_e32 v92, v92
	v_exp_f32_e32 v93, v93
	v_exp_f32_e32 v94, v94
	v_exp_f32_e32 v95, v95
	s_waitcnt lgkmcnt(2)
; #define AT_PVK(ks, VF) do { o0 = __builtin_amdgcn_mfma_f32_32x32x16_bf16(__builtin_bit_cast(bf16x8, pw[ks]), VF[0], o0, 0, 0, 0); \
;             o1 = __builtin_amdgcn_mfma_f32_32x32x16_bf16(__builtin_bit_cast(bf16x8, pw[ks]), VF[1], o1, 0, 0, 0); \
;             ol = __builtin_amdgcn_mfma_f32_32x32x16_bf16(__builtin_bit_cast(bf16x8, pw[ks]), ones, ol, 0, 0, 0); } while (0)
; template <int DK>
; __device__ __forceinline__ void attn_unit(LAS unsigned char* lds, const GAS bf16* Qp, const GAS bf16* Kp, const GAS bf16* Vp, GAS bf16* Yp, int b, int j, int nkeys, int tid, int lane, int wave) {
;     ...
; #pragma unroll
;           for (int q4 = 0; q4 < 4; ++q4) {
;               vfb[0] = AT_VF(0, 2 * q4 + 1); vfb[1] = AT_VF(1, 2 * q4 + 1);
;               AT_PVK(2 * q4, vfa);
;               if (q4 + 1 < 4) { AT_EXPQ(q4 + 1); vfa[0] = AT_VF(0, 2 * q4 + 2); vfa[1] = AT_VF(1, 2 * q4 + 2); }
;               AT_PVK(2 * q4 + 1, vfb);
;               __builtin_amdgcn_sched_barrier(0);
;           }
;     ...
;         }
;         __syncthreads();
	v_mfma_f32_32x32x16_bf16 v[34:49], v[98:101], v[126:129], v[34:49]
	v_exp_f32_e32 v96, v96
	v_exp_f32_e32 v97, v97
	v_pk_add_f32 v[2:3], v[2:3], v[90:91]
	v_pk_add_f32 v[4:5], v[4:5], v[92:93]
	v_pk_add_f32 v[6:7], v[6:7], v[94:95]
	v_pk_add_f32 v[8:9], v[8:9], v[96:97]
	v_cvt_pk_bf16_f32 v90, v90, v91
	v_cvt_pk_bf16_f32 v91, v92, v93
	v_cvt_pk_bf16_f32 v92, v94, v95
	v_cvt_pk_bf16_f32 v93, v96, v97
	ds_read_b64_tr_b16 v[94:95], v0 offset:57344
	ds_read_b64_tr_b16 v[96:97], v0 offset:57856
	s_nop 0
	v_exp_f32_e32 v82, v82
	v_exp_f32_e32 v83, v83
	v_exp_f32_e32 v84, v84
	v_exp_f32_e32 v85, v85
	v_exp_f32_e32 v86, v86
	v_exp_f32_e32 v87, v87
	v_exp_f32_e32 v88, v88
	s_waitcnt lgkmcnt(2)
	v_mfma_f32_32x32x16_bf16 v[18:33], v[106:109], v[102:105], v[18:33]
	ds_read_b64_tr_b16 v[98:99], v0 offset:64512
	ds_read_b64_tr_b16 v[100:101], v0 offset:65024
	ds_read_b64_tr_b16 v[102:103], v170 offset:12288
	ds_read_b64_tr_b16 v[104:105], v170 offset:12800
	v_exp_f32_e32 v89, v89
	v_pk_add_f32 v[2:3], v[2:3], v[82:83]
	v_pk_add_f32 v[4:5], v[4:5], v[84:85]
	v_pk_add_f32 v[6:7], v[6:7], v[86:87]
	v_pk_add_f32 v[8:9], v[8:9], v[88:89]
	v_cvt_pk_bf16_f32 v82, v82, v83
	v_cvt_pk_bf16_f32 v83, v84, v85
	v_cvt_pk_bf16_f32 v84, v86, v87
	v_cvt_pk_bf16_f32 v85, v88, v89
	s_waitcnt lgkmcnt(2)
	v_mfma_f32_32x32x16_bf16 v[34:49], v[106:109], v[98:101], v[34:49]
	s_nop 0
	v_mfma_f32_32x32x16_bf16 v[18:33], v[82:85], v[94:97], v[18:33]
	ds_read_b64_tr_b16 v[86:87], v0 offset:58368
	ds_read_b64_tr_b16 v[88:89], v0 offset:58880
	v_exp_f32_e32 v74, v74
	v_exp_f32_e32 v75, v75
	v_exp_f32_e32 v76, v76
	v_exp_f32_e32 v77, v77
	v_exp_f32_e32 v78, v78
	v_exp_f32_e32 v79, v79
	s_waitcnt lgkmcnt(2)
	v_mfma_f32_32x32x16_bf16 v[34:49], v[82:85], v[102:105], v[34:49]
	v_exp_f32_e32 v80, v80
	v_exp_f32_e32 v81, v81
	v_pk_add_f32 v[2:3], v[2:3], v[74:75]
	v_pk_add_f32 v[4:5], v[4:5], v[76:77]
	v_pk_add_f32 v[6:7], v[6:7], v[78:79]
	v_pk_add_f32 v[8:9], v[8:9], v[80:81]
	v_cvt_pk_bf16_f32 v74, v74, v75
	v_cvt_pk_bf16_f32 v75, v76, v77
	v_cvt_pk_bf16_f32 v76, v78, v79
	v_cvt_pk_bf16_f32 v77, v80, v81
	ds_read_b64_tr_b16 v[78:79], v0 offset:59392
	ds_read_b64_tr_b16 v[80:81], v0 offset:59904
	s_nop 0
	v_exp_f32_e32 v66, v66
	v_exp_f32_e32 v67, v67
	v_exp_f32_e32 v68, v68
	v_exp_f32_e32 v69, v69
	v_exp_f32_e32 v70, v70
	v_exp_f32_e32 v71, v71
	v_exp_f32_e32 v72, v72
	s_waitcnt lgkmcnt(2)
	v_mfma_f32_32x32x16_bf16 v[18:33], v[90:93], v[86:89], v[18:33]
	ds_read_b64_tr_b16 v[82:83], v170 offset:13312
	ds_read_b64_tr_b16 v[84:85], v170 offset:13824
	ds_read_b64_tr_b16 v[86:87], v170 offset:14336
	ds_read_b64_tr_b16 v[88:89], v170 offset:14848
	v_exp_f32_e32 v73, v73
	v_pk_add_f32 v[2:3], v[2:3], v[66:67]
	v_pk_add_f32 v[4:5], v[4:5], v[68:69]
	v_pk_add_f32 v[6:7], v[6:7], v[70:71]
	v_pk_add_f32 v[8:9], v[8:9], v[72:73]
	v_cvt_pk_bf16_f32 v66, v66, v67
	v_cvt_pk_bf16_f32 v67, v68, v69
	v_cvt_pk_bf16_f32 v68, v70, v71
	v_cvt_pk_bf16_f32 v69, v72, v73
	s_waitcnt lgkmcnt(2)
	v_mfma_f32_32x32x16_bf16 v[34:49], v[90:93], v[82:85], v[34:49]
	s_nop 0
	v_mfma_f32_32x32x16_bf16 v[18:33], v[66:69], v[78:81], v[18:33]
	s_waitcnt lgkmcnt(0)
	v_mfma_f32_32x32x16_bf16 v[34:49], v[66:69], v[86:89], v[34:49]
	s_nop 0
	ds_read_b64_tr_b16 v[66:67], v0 offset:60416
	ds_read_b64_tr_b16 v[68:69], v0 offset:60928
	ds_read_b64_tr_b16 v[70:71], v170 offset:15360
	ds_read_b64_tr_b16 v[72:73], v170 offset:15872
	s_waitcnt lgkmcnt(2)
	v_mfma_f32_32x32x16_bf16 v[18:33], v[74:77], v[66:69], v[18:33]
	s_waitcnt lgkmcnt(0)
	v_mfma_f32_32x32x16_bf16 v[34:49], v[74:77], v[70:73], v[34:49]
	s_nop 0
	s_add_u32 s22, s22, 0x4000
	s_addc_u32 s23, s23, 0
	s_add_i32 s7, s7, 1
	s_cmp_lg_u32 s6, s22
	s_barrier
	s_cbranch_scc0 .LBB0_166

; #define LAS __attribute__((address_space(3)))
; #define AT_LOAD(t) do { const GAS u32x4* Kg_ = (const GAS u32x4*)(Kp + (size_t)(t) * 128 * DK); const GAS u32x4* Vg_ = (const GAS u32x4*)(Vp + (size_t)(t) * 128 * 64); \
;         _Pragma("unroll") for (int i_ = 0; i_ < NKC; ++i_) kreg[i_] = Kg_[tid + 512 * i_]; vreg[0] = Vg_[tid]; vreg[1] = Vg_[tid + 512]; } while (0)
; #define AT_STORE(bf_) do { LAS unsigned char* nb_ = lds + (bf_) * AT_KBUF; _Pragma("unroll") for (int i_ = 0; i_ < NKC; ++i_) *(LAS u32x4*)(nb_ + koff[i_]) = kreg[i_]; \
;         *(LAS u32x4*)(lds + (bf_) * AT_VBUF + voff[0]) = vreg[0]; *(LAS u32x4*)(lds + (bf_) * AT_VBUF + voff[1]) = vreg[1]; } while (0)
; template <int DK>
; __device__ __forceinline__ void attn_unit(LAS unsigned char* lds, const GAS bf16* Qp, const GAS bf16* Kp, const GAS bf16* Vp, GAS bf16* Yp, int b, int j, int nkeys, int tid, int lane, int wave) {
;     ...
;         { LAS unsigned char* kb = lds + cur * AT_KBUF + kfo;
;           bf16x8 ka[2][4];
; #pragma unroll
;           for (int q4 = 0; q4 < 4; ++q4) ka[0][q4] = *(LAS bf16x8*)(kb + q4 * 32 * KSTR);
; #pragma unroll
;           for (int d0 = 0; d0 < ND; ++d0) {
;               if (d0 + 1 < ND) {
; #pragma unroll
;                   for (int q4 = 0; q4 < 4; ++q4) ka[(d0 + 1) & 1][q4] = *(LAS bf16x8*)(kb + q4 * 32 * KSTR + (d0 + 1) * 32);
;               }
; #pragma unroll
;               for (int q4 = 0; q4 < 4; ++q4) p[q4] = __builtin_amdgcn_mfma_f32_32x32x16_bf16(ka[d0 & 1][q4], qr[d0], d0 == 0 ? negm : p[q4], 0, 0, 0);
;               if (d0 == 0) { if (t + 1 < NT) AT_STORE(cur ^ 1); if (t + 2 < NT) AT_LOAD(t + 2); }
;               __builtin_amdgcn_sched_barrier(0);
;           } }
;         float rma = fmaxf(p[0][0], p[1][0]), rmb = fmaxf(p[2][0], p[3][0]);
; #pragma unroll
;         for (int r = 1; r < 16; ++r) { rma = fmaxf(fmaxf(rma, p[0][r]), p[1][r]); rmb = fmaxf(fmaxf(rmb, p[2][r]), p[3][r]); }
;         float rm = fmaxf(rma, rmb);
;         { const unsigned ru_ = __builtin_bit_cast(unsigned, rm); auto rr_ = __builtin_amdgcn_permlane32_swap(ru_, ru_, false, false);
;           rm = fmaxf(__builtin_bit_cast(float, (unsigned)rr_[0]), __builtin_bit_cast(float, (unsigned)rr_[1])); }
;         if (t == 0 || __any(rm > 8.0f)) {
;             const float dl = (t == 0) ? rm : fmaxf(rm, 0.f), f = __builtin_amdgcn_exp2f(-dl);
.LBB0_163:
	v_mfma_f32_32x32x16_bf16 v[114:129], v[162:165], v[134:137], v[114:129]
	v_mfma_f32_32x32x16_bf16 v[98:113], v[166:169], v[134:137], v[98:113]
	v_mfma_f32_32x32x16_bf16 v[82:97], v[170:173], v[134:137], v[82:97]
	ds_read_b128 v[162:165], v0 offset:64
	ds_read_b128 v[166:169], v0 offset:4672
	ds_read_b128 v[170:173], v0 offset:9280
	ds_read_b128 v[186:189], v0 offset:13888
	s_waitcnt lgkmcnt(4)
	v_mfma_f32_32x32x16_bf16 v[66:81], v[174:177], v[134:137], v[66:81]
	s_waitcnt lgkmcnt(3)
	v_mfma_f32_32x32x16_bf16 v[114:129], v[162:165], v[138:141], v[114:129]
	s_waitcnt lgkmcnt(2)
	v_mfma_f32_32x32x16_bf16 v[98:113], v[166:169], v[138:141], v[98:113]
	s_waitcnt lgkmcnt(1)
	v_mfma_f32_32x32x16_bf16 v[82:97], v[170:173], v[138:141], v[82:97]
	ds_read_b128 v[162:165], v0 offset:96
	ds_read_b128 v[166:169], v0 offset:4704
	ds_read_b128 v[170:173], v0 offset:9312
	ds_read_b128 v[174:177], v0 offset:13920
	s_waitcnt lgkmcnt(4)
	v_mfma_f32_32x32x16_bf16 v[66:81], v[186:189], v[138:141], v[66:81]
	s_waitcnt lgkmcnt(3)
	v_mfma_f32_32x32x16_bf16 v[114:129], v[162:165], v[142:145], v[114:129]
	s_waitcnt lgkmcnt(2)
	v_mfma_f32_32x32x16_bf16 v[98:113], v[166:169], v[142:145], v[98:113]
	s_waitcnt lgkmcnt(1)
	v_mfma_f32_32x32x16_bf16 v[82:97], v[170:173], v[142:145], v[82:97]
	s_waitcnt lgkmcnt(0)
	v_mfma_f32_32x32x16_bf16 v[66:81], v[174:177], v[142:145], v[66:81]
	s_nop 11
	v_max_f32_e32 v0, v66, v66
	v_max_f32_e32 v162, v82, v82
	v_max_f32_e32 v0, v162, v0
	v_max3_f32 v162, v114, v98, v115
	v_max3_f32 v0, v0, v83, v67
	v_max3_f32 v162, v162, v99, v116
	v_max3_f32 v0, v0, v84, v68
	v_max3_f32 v162, v162, v100, v117
	v_max3_f32 v0, v0, v85, v69
	v_max3_f32 v162, v162, v101, v118
	v_max3_f32 v0, v0, v86, v70
	v_max3_f32 v162, v162, v102, v119
	v_max3_f32 v0, v0, v87, v71
	v_max3_f32 v162, v162, v103, v120
	v_max3_f32 v0, v0, v88, v72
	v_max3_f32 v162, v162, v104, v121
	v_max3_f32 v0, v0, v89, v73
	v_max3_f32 v162, v162, v105, v122
	v_max3_f32 v0, v0, v90, v74
	v_max3_f32 v162, v162, v106, v123
	v_max3_f32 v0, v0, v91, v75
	v_max3_f32 v162, v162, v107, v124
	v_max3_f32 v0, v0, v92, v76
	v_max3_f32 v162, v162, v108, v125
	v_max3_f32 v0, v0, v93, v77
	v_max3_f32 v162, v162, v109, v126
	v_max3_f32 v0, v0, v94, v78
	v_max3_f32 v162, v162, v110, v127
	v_max3_f32 v0, v0, v95, v79
	v_max3_f32 v162, v162, v111, v128
	v_max3_f32 v0, v0, v96, v80
	v_max3_f32 v162, v162, v112, v129
	v_max3_f32 v0, v0, v97, v81
	v_max3_f32 v0, v162, v113, v0
	v_mov_b32_e32 v162, v0
	s_nop 1
	v_permlane32_swap_b32_e32 v0, v162
	v_max_f32_e32 v162, v162, v162
	v_max_f32_e32 v0, v0, v0
	v_max_f32_e32 v0, v0, v162
	v_cmp_lt_f32_e32 vcc, s33, v0
	s_cbranch_vccz .LBB0_158
	v_max_f32_e32 v0, v0, v0
	v_max_f32_e32 v0, 0, v0
	v_exp_f32_e64 v10, -v0
	s_and_saveexec_b64 s[46:47], s[40:41]
	s_cbranch_execz .LBB0_157
	v_exp_f32_e64 v50, -v0
	ds_write_b32 v238, v50
	s_branch .LBB0_157
.LBB0_166:
	v_pk_add_f32 v[2:3], v[2:3], v[4:5]
	v_pk_add_f32 v[6:7], v[6:7], v[8:9]
	v_pk_add_f32 v[2:3], v[2:3], v[6:7]
	v_add_f32_e32 v2, v2, v3
	v_mov_b32_e32 v3, v2
	s_nop 1
	v_permlane32_swap_b32_e32 v2, v3
	v_add_f32_e32 v2, v2, v3
	v_add_u32_e32 v66, s63, v236
	ds_write_b32 v238, v2
	s_waitcnt lgkmcnt(0)
	ds_read_b128 v[2:5], v66
	ds_read_b128 v[6:9], v66 offset:32
	ds_read_b128 v[10:13], v66 offset:64
	ds_read_b128 v[14:17], v66 offset:96
	s_waitcnt lgkmcnt(0)
; #define GAS __attribute__((address_space(1)))
; __device__ __forceinline__ unsigned f2bf(float f) { unsigned u = __builtin_bit_cast(unsigned, f); return (u + 0x7fffu + ((u >> 16) & 1u)) >> 16; }
; __device__ __forceinline__ int crow(int r, int hi) { return (r & 3) + 8 * (r >> 2) + 4 * hi; }
; template <int DK>
; __device__ __forceinline__ void attn_unit(LAS unsigned char* lds, const GAS bf16* Qp, const GAS bf16* Kp, const GAS bf16* Vp, GAS bf16* Yp, int b, int j, int nkeys, int tid, int lane, int wave) {
;     ...
;     const int pos0 = 256 * j + wave * 32;
; #pragma unroll
;     for (int r = 0; r < 16; ++r) {
;         const int qq = crow(r, hi); const float inv = __builtin_amdgcn_rcpf(ol[r]); const int pos = pos0 + qq;
;         const int row = (j == 0) ? MLAT + b * CTXL + pos : b * SEQ + pos - CTXL;
;         GAS bf16* yp = Yp + (size_t)row * DM + r32;
;         yp[0] = (bf16)f2bf(o0[r] * inv); yp[32] = (bf16)f2bf(o1[r] * inv);
;     }
	s_lshl_b32 s6, s74, 6
	s_ashr_i32 s7, s6, 31
	v_lshl_add_u64 v[50:51], s[6:7], 1, v[204:205]
	s_lshl_b32 s4, s73, 11
	s_lshl_b32 s6, s73, 8
	s_addk_i32 s4, 0xff00
	s_add_i32 s8, s6, 0x4000
	v_rcp_f32_e32 v0, v2
	s_and_b64 s[6:7], s[44:45], exec
	s_cselect_b32 s4, s8, s4
	s_add_i32 s4, s4, s5
	v_add_u32_e32 v52, s4, v239
	v_ashrrev_i32_e32 v53, 31, v52
	v_mul_f32_e32 v2, v18, v0
	v_lshlrev_b64 v[54:55], 11, v[52:53]
	v_bfe_u32 v18, v2, 16, 1
	v_lshl_add_u64 v[54:55], v[50:51], 0, v[54:55]
	v_add3_u32 v2, v2, v18, s3
	v_mul_f32_e32 v0, v34, v0
	global_store_short_d16_hi v[54:55], v2, off
	v_bfe_u32 v2, v0, 16, 1
	v_add3_u32 v0, v0, v2, s3
	global_store_short_d16_hi v[54:55], v0, off offset:64
	v_rcp_f32_e32 v0, v3
	v_or_b32_e32 v2, 1, v52
	v_ashrrev_i32_e32 v3, 31, v2
	v_lshlrev_b64 v[2:3], 11, v[2:3]
	v_mul_f32_e32 v18, v19, v0
	v_bfe_u32 v19, v18, 16, 1
	v_lshl_add_u64 v[2:3], v[50:51], 0, v[2:3]
	v_add3_u32 v18, v18, v19, s3
	v_mul_f32_e32 v0, v35, v0
	global_store_short_d16_hi v[2:3], v18, off
	v_bfe_u32 v18, v0, 16, 1
	v_add3_u32 v0, v0, v18, s3
	global_store_short_d16_hi v[2:3], v0, off offset:64
	v_rcp_f32_e32 v0, v4
	v_or_b32_e32 v2, 2, v52
	v_ashrrev_i32_e32 v3, 31, v2
	v_lshlrev_b64 v[2:3], 11, v[2:3]
	v_mul_f32_e32 v4, v20, v0
	v_bfe_u32 v18, v4, 16, 1
	v_lshl_add_u64 v[2:3], v[50:51], 0, v[2:3]
	v_add3_u32 v4, v4, v18, s3
	v_mul_f32_e32 v0, v36, v0
	global_store_short_d16_hi v[2:3], v4, off
	v_bfe_u32 v4, v0, 16, 1
	v_add3_u32 v0, v0, v4, s3
	global_store_short_d16_hi v[2:3], v0, off offset:64
	v_rcp_f32_e32 v0, v5
	v_or_b32_e32 v2, 3, v52
	v_ashrrev_i32_e32 v3, 31, v2
	v_lshlrev_b64 v[2:3], 11, v[2:3]
	v_mul_f32_e32 v4, v21, v0
	v_bfe_u32 v5, v4, 16, 1
	v_lshl_add_u64 v[2:3], v[50:51], 0, v[2:3]
	v_add3_u32 v4, v4, v5, s3
	v_mul_f32_e32 v0, v37, v0
	global_store_short_d16_hi v[2:3], v4, off
	v_bfe_u32 v4, v0, 16, 1
	v_add3_u32 v0, v0, v4, s3
	global_store_short_d16_hi v[2:3], v0, off offset:64
	v_rcp_f32_e32 v0, v6
	v_add_u32_e32 v2, 8, v52
	v_ashrrev_i32_e32 v3, 31, v2
	v_lshlrev_b64 v[2:3], 11, v[2:3]
	v_mul_f32_e32 v4, v22, v0
	v_bfe_u32 v5, v4, 16, 1
	v_lshl_add_u64 v[2:3], v[50:51], 0, v[2:3]
	v_add3_u32 v4, v4, v5, s3
	v_mul_f32_e32 v0, v38, v0
	global_store_short_d16_hi v[2:3], v4, off
	v_bfe_u32 v4, v0, 16, 1
	v_add3_u32 v0, v0, v4, s3
	global_store_short_d16_hi v[2:3], v0, off offset:64
	v_rcp_f32_e32 v0, v7
	v_add_u32_e32 v2, 9, v52
	v_ashrrev_i32_e32 v3, 31, v2
	v_lshlrev_b64 v[2:3], 11, v[2:3]
	v_mul_f32_e32 v4, v23, v0
	v_bfe_u32 v5, v4, 16, 1
	v_lshl_add_u64 v[2:3], v[50:51], 0, v[2:3]
	v_add3_u32 v4, v4, v5, s3
	v_mul_f32_e32 v0, v39, v0
	global_store_short_d16_hi v[2:3], v4, off
	v_bfe_u32 v4, v0, 16, 1
	v_add3_u32 v0, v0, v4, s3
	global_store_short_d16_hi v[2:3], v0, off offset:64
	v_rcp_f32_e32 v0, v8
	v_add_u32_e32 v2, 10, v52
	v_ashrrev_i32_e32 v3, 31, v2
	v_lshlrev_b64 v[2:3], 11, v[2:3]
	v_mul_f32_e32 v4, v24, v0
	v_bfe_u32 v5, v4, 16, 1
	v_lshl_add_u64 v[2:3], v[50:51], 0, v[2:3]
	v_add3_u32 v4, v4, v5, s3
	v_mul_f32_e32 v0, v40, v0
	global_store_short_d16_hi v[2:3], v4, off
	v_bfe_u32 v4, v0, 16, 1
	v_add3_u32 v0, v0, v4, s3
	global_store_short_d16_hi v[2:3], v0, off offset:64
	v_rcp_f32_e32 v0, v9
	v_add_u32_e32 v2, 11, v52
	v_ashrrev_i32_e32 v3, 31, v2
	v_lshlrev_b64 v[2:3], 11, v[2:3]
	v_mul_f32_e32 v4, v25, v0
	v_bfe_u32 v5, v4, 16, 1
	v_lshl_add_u64 v[2:3], v[50:51], 0, v[2:3]
	v_add3_u32 v4, v4, v5, s3
	v_mul_f32_e32 v0, v41, v0
	global_store_short_d16_hi v[2:3], v4, off
	v_bfe_u32 v4, v0, 16, 1
	v_add3_u32 v0, v0, v4, s3
	global_store_short_d16_hi v[2:3], v0, off offset:64
	v_rcp_f32_e32 v0, v10
	v_add_u32_e32 v2, 16, v52
	v_ashrrev_i32_e32 v3, 31, v2
	v_lshlrev_b64 v[2:3], 11, v[2:3]
	v_mul_f32_e32 v4, v26, v0
	v_bfe_u32 v5, v4, 16, 1
	v_lshl_add_u64 v[2:3], v[50:51], 0, v[2:3]
	v_add3_u32 v4, v4, v5, s3
	v_mul_f32_e32 v0, v42, v0
	global_store_short_d16_hi v[2:3], v4, off
	v_bfe_u32 v4, v0, 16, 1
	v_add3_u32 v0, v0, v4, s3
	global_store_short_d16_hi v[2:3], v0, off offset:64
	v_rcp_f32_e32 v0, v11
	v_add_u32_e32 v2, 17, v52
	v_ashrrev_i32_e32 v3, 31, v2
	v_lshlrev_b64 v[2:3], 11, v[2:3]
	v_mul_f32_e32 v4, v27, v0
	v_bfe_u32 v5, v4, 16, 1
	v_lshl_add_u64 v[2:3], v[50:51], 0, v[2:3]
	v_add3_u32 v4, v4, v5, s3
	v_mul_f32_e32 v0, v43, v0
	global_store_short_d16_hi v[2:3], v4, off
	v_bfe_u32 v4, v0, 16, 1
	v_add3_u32 v0, v0, v4, s3
	global_store_short_d16_hi v[2:3], v0, off offset:64
	v_rcp_f32_e32 v0, v12
	v_add_u32_e32 v2, 18, v52
	v_ashrrev_i32_e32 v3, 31, v2
	v_lshlrev_b64 v[2:3], 11, v[2:3]
	v_mul_f32_e32 v4, v28, v0
	v_bfe_u32 v5, v4, 16, 1
	v_lshl_add_u64 v[2:3], v[50:51], 0, v[2:3]
	v_add3_u32 v4, v4, v5, s3
	v_mul_f32_e32 v0, v44, v0
	global_store_short_d16_hi v[2:3], v4, off
	v_bfe_u32 v4, v0, 16, 1
	v_add3_u32 v0, v0, v4, s3
	global_store_short_d16_hi v[2:3], v0, off offset:64
	v_rcp_f32_e32 v0, v13
	v_add_u32_e32 v2, 19, v52
	v_ashrrev_i32_e32 v3, 31, v2
	v_lshlrev_b64 v[2:3], 11, v[2:3]
	v_mul_f32_e32 v4, v29, v0
	v_bfe_u32 v5, v4, 16, 1
	v_lshl_add_u64 v[2:3], v[50:51], 0, v[2:3]
	v_add3_u32 v4, v4, v5, s3
	v_mul_f32_e32 v0, v45, v0
	global_store_short_d16_hi v[2:3], v4, off
	v_bfe_u32 v4, v0, 16, 1
	v_add3_u32 v0, v0, v4, s3
	global_store_short_d16_hi v[2:3], v0, off offset:64
	v_rcp_f32_e32 v0, v14
	v_add_u32_e32 v2, 24, v52
	v_ashrrev_i32_e32 v3, 31, v2
	v_lshlrev_b64 v[2:3], 11, v[2:3]
	v_mul_f32_e32 v4, v30, v0
	v_bfe_u32 v5, v4, 16, 1
	v_lshl_add_u64 v[2:3], v[50:51], 0, v[2:3]
	v_add3_u32 v4, v4, v5, s3
	v_mul_f32_e32 v0, v46, v0
	global_store_short_d16_hi v[2:3], v4, off
	v_bfe_u32 v4, v0, 16, 1
	v_add3_u32 v0, v0, v4, s3
	global_store_short_d16_hi v[2:3], v0, off offset:64
	v_rcp_f32_e32 v0, v15
	v_add_u32_e32 v2, 25, v52
	v_ashrrev_i32_e32 v3, 31, v2
	v_lshlrev_b64 v[2:3], 11, v[2:3]
	v_mul_f32_e32 v4, v31, v0
	v_bfe_u32 v5, v4, 16, 1
	v_lshl_add_u64 v[2:3], v[50:51], 0, v[2:3]
	v_add3_u32 v4, v4, v5, s3
	v_mul_f32_e32 v0, v47, v0
	global_store_short_d16_hi v[2:3], v4, off
	v_bfe_u32 v4, v0, 16, 1
	v_add3_u32 v0, v0, v4, s3
	global_store_short_d16_hi v[2:3], v0, off offset:64
	v_rcp_f32_e32 v0, v16
	v_add_u32_e32 v2, 26, v52
	v_ashrrev_i32_e32 v3, 31, v2
	v_lshlrev_b64 v[2:3], 11, v[2:3]
	v_mul_f32_e32 v4, v32, v0
	v_bfe_u32 v5, v4, 16, 1
	v_lshl_add_u64 v[2:3], v[50:51], 0, v[2:3]
	v_add3_u32 v4, v4, v5, s3
	v_mul_f32_e32 v0, v48, v0
	global_store_short_d16_hi v[2:3], v4, off
	v_bfe_u32 v4, v0, 16, 1
	v_add3_u32 v0, v0, v4, s3
	global_store_short_d16_hi v[2:3], v0, off offset:64
	v_rcp_f32_e32 v0, v17
	v_add_u32_e32 v2, 27, v52
	v_ashrrev_i32_e32 v3, 31, v2
	v_lshlrev_b64 v[2:3], 11, v[2:3]
	v_mul_f32_e32 v4, v33, v0
	v_bfe_u32 v5, v4, 16, 1
	v_lshl_add_u64 v[2:3], v[50:51], 0, v[2:3]
	v_add3_u32 v4, v4, v5, s3
	v_mul_f32_e32 v0, v49, v0
	global_store_short_d16_hi v[2:3], v4, off
	v_bfe_u32 v4, v0, 16, 1
	v_add3_u32 v0, v0, v4, s3
	global_store_short_d16_hi v[2:3], v0, off offset:64
	s_waitcnt lgkmcnt(0)
	s_mov_b32 s7, 0
	s_barrier
